# MLA-projection epilogue: 8 rope-table loads prefetched per row group; split-K partial epilogue: gate loaded once, stores not waited on
# speedup vs baseline: 1.0285x; 1.0073x over previous
;     __device__ __forceinline__ void operator()(const f32x4 (&acc)[2][2][4][2], const Unit& u, int wr, int wc, int fr, int fq) const {
;     ...
;                     if (cg0 < 384) {
;                         const float rs = RSTD[row * 2];
; #pragma unroll
;                         for (int n = 0; n < 2; ++n)
; #pragma unroll
;                             for (int j = 0; j < 4; ++j) v[4 * n + j] = acc[ai][bj][m][n][j] * rs;
;                         const int d0 = cg0 % 96;
;                         if (d0 == 64) {
;                             const bool lat = row < RL; const int t = row & 8191; const int pos = (fq >> 1) ? (t & 63) : (t >> 6); const bool isx2 = fq & 1;
; #pragma unroll
;                             for (int e = 0; e < 8; ++e) {
;                                 const float pr = shflx(v[e], 16);
;                                 const float2 cs = RT[pos * 8 + e];
;                                 const float r = isx2 ? (pr * cs.y + v[e] * cs.x) : (v[e] * cs.x - pr * cs.y);
;                                 v[e] = lat ? r : v[e];
;                             }
;                         }
.LBB0_311:
	s_or_saveexec_b64 s[2:3], s[0:1]
	v_ashrrev_i32_e32 v143, 31, v142
	s_xor_b64 exec, exec, s[2:3]
	s_cbranch_execz .LBB0_315
	global_load_dword v130, v[150:151], off
	s_waitcnt vmcnt(0)
	v_pk_mul_f32 v[126:127], v[126:127], v[130:131] op_sel_hi:[1,0]
	v_pk_mul_f32 v[128:129], v[128:129], v[130:131] op_sel_hi:[1,0]
	v_pk_mul_f32 v[122:123], v[122:123], v[130:131] op_sel_hi:[1,0]
	v_pk_mul_f32 v[124:125], v[124:125], v[130:131] op_sel_hi:[1,0]
	s_and_saveexec_b64 s[0:1], s[10:11]
	s_xor_b64 s[0:1], exec, s[0:1]
	s_andn2_saveexec_b64 s[36:37], s[0:1]
	s_cbranch_execz .LBB0_314
	v_mov_b32_e32 v131, v220
	v_cndmask_b32_e64 v130, v157, v158, s[6:7]
	v_lshlrev_b32_e32 v131, 2, v131
	v_xor_b32_e32 v131, 64, v131
	v_lshlrev_b32_e32 v133, 6, v130
	ds_bpermute_b32 v132, v131, v126
	global_load_dwordx2 v[174:175], v133, s[26:27]
	global_load_dwordx2 v[176:177], v133, s[26:27] offset:8
	global_load_dwordx2 v[178:179], v133, s[26:27] offset:16
	global_load_dwordx2 v[180:181], v133, s[26:27] offset:24
	global_load_dwordx2 v[182:183], v133, s[26:27] offset:32
	global_load_dwordx2 v[184:185], v133, s[26:27] offset:40
	global_load_dwordx2 v[208:209], v133, s[26:27] offset:48
	global_load_dwordx2 v[210:211], v133, s[26:27] offset:56
	v_cmp_gt_i32_e64 s[14:15], s95, v144
	s_waitcnt vmcnt(7) lgkmcnt(0)
	v_mul_f32_e32 v131, v175, v132
	v_cndmask_b32_e64 v131, v131, -v131, vcc
	v_fmac_f32_e32 v131, v126, v174
	v_mov_b32_e32 v130, v220
	v_cndmask_b32_e64 v126, v126, v131, s[14:15]
	v_lshlrev_b32_e32 v130, 2, v130
	v_xor_b32_e32 v130, 64, v130
	ds_bpermute_b32 v132, v130, v127
	s_waitcnt vmcnt(6) lgkmcnt(0)
	v_mul_f32_e32 v131, v177, v132
	v_cndmask_b32_e64 v131, v131, -v131, vcc
	v_fmac_f32_e32 v131, v127, v176
	v_mov_b32_e32 v130, v220
	v_cndmask_b32_e64 v127, v127, v131, s[14:15]
	v_lshlrev_b32_e32 v130, 2, v130
	v_xor_b32_e32 v130, 64, v130
	ds_bpermute_b32 v132, v130, v128
	s_waitcnt vmcnt(5) lgkmcnt(0)
	v_mul_f32_e32 v131, v179, v132
	v_cndmask_b32_e64 v131, v131, -v131, vcc
	v_fmac_f32_e32 v131, v128, v178
	v_mov_b32_e32 v130, v220
	v_cndmask_b32_e64 v128, v128, v131, s[14:15]
	v_lshlrev_b32_e32 v130, 2, v130
	v_xor_b32_e32 v130, 64, v130
	ds_bpermute_b32 v132, v130, v129
	s_waitcnt vmcnt(4) lgkmcnt(0)
	v_mul_f32_e32 v131, v181, v132
	v_cndmask_b32_e64 v131, v131, -v131, vcc
	v_fmac_f32_e32 v131, v129, v180
	v_mov_b32_e32 v130, v220
	v_cndmask_b32_e64 v129, v129, v131, s[14:15]
	v_lshlrev_b32_e32 v130, 2, v130
	v_xor_b32_e32 v130, 64, v130
	ds_bpermute_b32 v132, v130, v122
	s_waitcnt vmcnt(3) lgkmcnt(0)
	v_mul_f32_e32 v131, v183, v132
	v_cndmask_b32_e64 v131, v131, -v131, vcc
	v_fmac_f32_e32 v131, v122, v182
	v_mov_b32_e32 v130, v220
	v_cndmask_b32_e64 v122, v122, v131, s[14:15]
	v_lshlrev_b32_e32 v130, 2, v130
	v_xor_b32_e32 v130, 64, v130
	ds_bpermute_b32 v132, v130, v123
	s_waitcnt vmcnt(2) lgkmcnt(0)
	v_mul_f32_e32 v131, v185, v132
	v_cndmask_b32_e64 v131, v131, -v131, vcc
	v_fmac_f32_e32 v131, v123, v184
	v_mov_b32_e32 v130, v220
	v_cndmask_b32_e64 v123, v123, v131, s[14:15]
	v_lshlrev_b32_e32 v130, 2, v130
	v_xor_b32_e32 v130, 64, v130
	ds_bpermute_b32 v132, v130, v124
	s_waitcnt vmcnt(1) lgkmcnt(0)
	v_mul_f32_e32 v131, v209, v132
	v_cndmask_b32_e64 v131, v131, -v131, vcc
	v_fmac_f32_e32 v131, v124, v208
	v_mov_b32_e32 v130, v220
	v_cndmask_b32_e64 v124, v124, v131, s[14:15]
	v_lshlrev_b32_e32 v130, 2, v130
	v_xor_b32_e32 v130, 64, v130
	ds_bpermute_b32 v132, v130, v125
	s_waitcnt vmcnt(0) lgkmcnt(0)
	v_mul_f32_e32 v131, v211, v132
	v_cndmask_b32_e64 v131, v131, -v131, vcc
	v_fmac_f32_e32 v131, v125, v210
	v_cndmask_b32_e64 v125, v125, v131, s[14:15]

;     __device__ __forceinline__ void operator()(const f32x4 (&acc)[2][2][4][2], const Unit& u, int wr, int wc, int fr, int fq) const {
;     ...
;                     if (cg0 < 384) {
;                         const float rs = RSTD[row * 2];
; #pragma unroll
;                         for (int n = 0; n < 2; ++n)
; #pragma unroll
;                             for (int j = 0; j < 4; ++j) v[4 * n + j] = acc[ai][bj][m][n][j] * rs;
;                         const int d0 = cg0 % 96;
;                         if (d0 == 64) {
;                             const bool lat = row < RL; const int t = row & 8191; const int pos = (fq >> 1) ? (t & 63) : (t >> 6); const bool isx2 = fq & 1;
; #pragma unroll
;                             for (int e = 0; e < 8; ++e) {
;                                 const float pr = shflx(v[e], 16);
;                                 const float2 cs = RT[pos * 8 + e];
;                                 const float r = isx2 ? (pr * cs.y + v[e] * cs.x) : (v[e] * cs.x - pr * cs.y);
;                                 v[e] = lat ? r : v[e];
;                             }
;                         }
.LBB0_321:
	s_andn2_saveexec_b64 s[2:3], s[0:1]
	s_cbranch_execz .LBB0_325
	global_load_dword v122, v[132:133], off
	s_waitcnt vmcnt(0)
	v_pk_mul_f32 v[118:119], v[118:119], v[122:123] op_sel_hi:[1,0]
	v_pk_mul_f32 v[120:121], v[120:121], v[122:123] op_sel_hi:[1,0]
	v_pk_mul_f32 v[114:115], v[114:115], v[122:123] op_sel_hi:[1,0]
	v_pk_mul_f32 v[116:117], v[116:117], v[122:123] op_sel_hi:[1,0]
	s_and_saveexec_b64 s[0:1], s[10:11]
	s_xor_b64 s[0:1], exec, s[0:1]
	s_andn2_saveexec_b64 s[36:37], s[0:1]
	s_cbranch_execz .LBB0_324
	v_mov_b32_e32 v123, v220
	v_cndmask_b32_e64 v122, v156, v158, s[6:7]
	v_lshlrev_b32_e32 v123, 2, v123
	v_xor_b32_e32 v123, 64, v123
	v_lshlrev_b32_e32 v125, 6, v122
	ds_bpermute_b32 v124, v123, v118
	global_load_dwordx2 v[174:175], v125, s[26:27]
	global_load_dwordx2 v[176:177], v125, s[26:27] offset:8
	global_load_dwordx2 v[178:179], v125, s[26:27] offset:16
	global_load_dwordx2 v[180:181], v125, s[26:27] offset:24
	global_load_dwordx2 v[182:183], v125, s[26:27] offset:32
	global_load_dwordx2 v[184:185], v125, s[26:27] offset:40
	global_load_dwordx2 v[208:209], v125, s[26:27] offset:48
	global_load_dwordx2 v[210:211], v125, s[26:27] offset:56
	v_cmp_gt_i32_e64 s[14:15], s95, v128
	s_waitcnt vmcnt(7) lgkmcnt(0)
	v_mul_f32_e32 v123, v175, v124
	v_cndmask_b32_e64 v123, v123, -v123, vcc
	v_fmac_f32_e32 v123, v118, v174
	v_mov_b32_e32 v122, v220
	v_cndmask_b32_e64 v118, v118, v123, s[14:15]
	v_lshlrev_b32_e32 v122, 2, v122
	v_xor_b32_e32 v122, 64, v122
	ds_bpermute_b32 v124, v122, v119
	s_waitcnt vmcnt(6) lgkmcnt(0)
	v_mul_f32_e32 v123, v177, v124
	v_cndmask_b32_e64 v123, v123, -v123, vcc
	v_fmac_f32_e32 v123, v119, v176
	v_mov_b32_e32 v122, v220
	v_cndmask_b32_e64 v119, v119, v123, s[14:15]
	v_lshlrev_b32_e32 v122, 2, v122
	v_xor_b32_e32 v122, 64, v122
	ds_bpermute_b32 v124, v122, v120
	s_waitcnt vmcnt(5) lgkmcnt(0)
	v_mul_f32_e32 v123, v179, v124
	v_cndmask_b32_e64 v123, v123, -v123, vcc
	v_fmac_f32_e32 v123, v120, v178
	v_mov_b32_e32 v122, v220
	v_cndmask_b32_e64 v120, v120, v123, s[14:15]
	v_lshlrev_b32_e32 v122, 2, v122
	v_xor_b32_e32 v122, 64, v122
	ds_bpermute_b32 v124, v122, v121
	s_waitcnt vmcnt(4) lgkmcnt(0)
	v_mul_f32_e32 v123, v181, v124
	v_cndmask_b32_e64 v123, v123, -v123, vcc
	v_fmac_f32_e32 v123, v121, v180
	v_mov_b32_e32 v122, v220
	v_cndmask_b32_e64 v121, v121, v123, s[14:15]
	v_lshlrev_b32_e32 v122, 2, v122
	v_xor_b32_e32 v122, 64, v122
	ds_bpermute_b32 v124, v122, v114
	s_waitcnt vmcnt(3) lgkmcnt(0)
	v_mul_f32_e32 v123, v183, v124
	v_cndmask_b32_e64 v123, v123, -v123, vcc
	v_fmac_f32_e32 v123, v114, v182
	v_mov_b32_e32 v122, v220
	v_cndmask_b32_e64 v114, v114, v123, s[14:15]
	v_lshlrev_b32_e32 v122, 2, v122
	v_xor_b32_e32 v122, 64, v122
	ds_bpermute_b32 v124, v122, v115
	s_waitcnt vmcnt(2) lgkmcnt(0)
	v_mul_f32_e32 v123, v185, v124
	v_cndmask_b32_e64 v123, v123, -v123, vcc
	v_fmac_f32_e32 v123, v115, v184
	v_mov_b32_e32 v122, v220
	v_cndmask_b32_e64 v115, v115, v123, s[14:15]
	v_lshlrev_b32_e32 v122, 2, v122
	v_xor_b32_e32 v122, 64, v122
	ds_bpermute_b32 v124, v122, v116
	s_waitcnt vmcnt(1) lgkmcnt(0)
	v_mul_f32_e32 v123, v209, v124
	v_cndmask_b32_e64 v123, v123, -v123, vcc
	v_fmac_f32_e32 v123, v116, v208
	v_mov_b32_e32 v122, v220
	v_cndmask_b32_e64 v116, v116, v123, s[14:15]
	v_lshlrev_b32_e32 v122, 2, v122
	v_xor_b32_e32 v122, 64, v122
	ds_bpermute_b32 v124, v122, v117
	s_waitcnt vmcnt(0) lgkmcnt(0)
	v_mul_f32_e32 v123, v211, v124
	v_cndmask_b32_e64 v123, v123, -v123, vcc
	v_fmac_f32_e32 v123, v117, v210
	v_cndmask_b32_e64 v117, v117, v123, s[14:15]

;     __device__ __forceinline__ void operator()(const f32x4 (&acc)[2][2][4][2], const Unit& u, int wr, int wc, int fr, int fq) const {
;     ...
;                     if (cg0 < 384) {
;                         const float rs = RSTD[row * 2];
; #pragma unroll
;                         for (int n = 0; n < 2; ++n)
; #pragma unroll
;                             for (int j = 0; j < 4; ++j) v[4 * n + j] = acc[ai][bj][m][n][j] * rs;
;                         const int d0 = cg0 % 96;
;                         if (d0 == 64) {
;                             const bool lat = row < RL; const int t = row & 8191; const int pos = (fq >> 1) ? (t & 63) : (t >> 6); const bool isx2 = fq & 1;
; #pragma unroll
;                             for (int e = 0; e < 8; ++e) {
;                                 const float pr = shflx(v[e], 16);
;                                 const float2 cs = RT[pos * 8 + e];
;                                 const float r = isx2 ? (pr * cs.y + v[e] * cs.x) : (v[e] * cs.x - pr * cs.y);
;                                 v[e] = lat ? r : v[e];
;                             }
;                         }
.LBB0_331:
	s_andn2_saveexec_b64 s[2:3], s[0:1]
	s_cbranch_execz .LBB0_335
	global_load_dword v114, v[122:123], off
	s_waitcnt vmcnt(0)
	v_pk_mul_f32 v[110:111], v[110:111], v[114:115] op_sel_hi:[1,0]
	v_pk_mul_f32 v[112:113], v[112:113], v[114:115] op_sel_hi:[1,0]
	v_pk_mul_f32 v[106:107], v[106:107], v[114:115] op_sel_hi:[1,0]
	v_pk_mul_f32 v[108:109], v[108:109], v[114:115] op_sel_hi:[1,0]
	s_and_saveexec_b64 s[0:1], s[10:11]
	s_xor_b64 s[0:1], exec, s[0:1]
	s_andn2_saveexec_b64 s[36:37], s[0:1]
	s_cbranch_execz .LBB0_334
	v_mov_b32_e32 v115, v220
	v_cndmask_b32_e64 v114, v155, v158, s[6:7]
	v_lshlrev_b32_e32 v115, 2, v115
	v_xor_b32_e32 v115, 64, v115
	v_lshlrev_b32_e32 v117, 6, v114
	ds_bpermute_b32 v116, v115, v110
	global_load_dwordx2 v[174:175], v117, s[26:27]
	global_load_dwordx2 v[176:177], v117, s[26:27] offset:8
	global_load_dwordx2 v[178:179], v117, s[26:27] offset:16
	global_load_dwordx2 v[180:181], v117, s[26:27] offset:24
	global_load_dwordx2 v[182:183], v117, s[26:27] offset:32
	global_load_dwordx2 v[184:185], v117, s[26:27] offset:40
	global_load_dwordx2 v[208:209], v117, s[26:27] offset:48
	global_load_dwordx2 v[210:211], v117, s[26:27] offset:56
	v_cmp_gt_i32_e64 s[14:15], s95, v118
	s_waitcnt vmcnt(7) lgkmcnt(0)
	v_mul_f32_e32 v115, v175, v116
	v_cndmask_b32_e64 v115, v115, -v115, vcc
	v_fmac_f32_e32 v115, v110, v174
	v_mov_b32_e32 v114, v220
	v_cndmask_b32_e64 v110, v110, v115, s[14:15]
	v_lshlrev_b32_e32 v114, 2, v114
	v_xor_b32_e32 v114, 64, v114
	ds_bpermute_b32 v116, v114, v111
	s_waitcnt vmcnt(6) lgkmcnt(0)
	v_mul_f32_e32 v115, v177, v116
	v_cndmask_b32_e64 v115, v115, -v115, vcc
	v_fmac_f32_e32 v115, v111, v176
	v_mov_b32_e32 v114, v220
	v_cndmask_b32_e64 v111, v111, v115, s[14:15]
	v_lshlrev_b32_e32 v114, 2, v114
	v_xor_b32_e32 v114, 64, v114
	ds_bpermute_b32 v116, v114, v112
	s_waitcnt vmcnt(5) lgkmcnt(0)
	v_mul_f32_e32 v115, v179, v116
	v_cndmask_b32_e64 v115, v115, -v115, vcc
	v_fmac_f32_e32 v115, v112, v178
	v_mov_b32_e32 v114, v220
	v_cndmask_b32_e64 v112, v112, v115, s[14:15]
	v_lshlrev_b32_e32 v114, 2, v114
	v_xor_b32_e32 v114, 64, v114
	ds_bpermute_b32 v116, v114, v113
	s_waitcnt vmcnt(4) lgkmcnt(0)
	v_mul_f32_e32 v115, v181, v116
	v_cndmask_b32_e64 v115, v115, -v115, vcc
	v_fmac_f32_e32 v115, v113, v180
	v_mov_b32_e32 v114, v220
	v_cndmask_b32_e64 v113, v113, v115, s[14:15]
	v_lshlrev_b32_e32 v114, 2, v114
	v_xor_b32_e32 v114, 64, v114
	ds_bpermute_b32 v116, v114, v106
	s_waitcnt vmcnt(3) lgkmcnt(0)
	v_mul_f32_e32 v115, v183, v116
	v_cndmask_b32_e64 v115, v115, -v115, vcc
	v_fmac_f32_e32 v115, v106, v182
	v_mov_b32_e32 v114, v220
	v_cndmask_b32_e64 v106, v106, v115, s[14:15]
	v_lshlrev_b32_e32 v114, 2, v114
	v_xor_b32_e32 v114, 64, v114
	ds_bpermute_b32 v116, v114, v107
	s_waitcnt vmcnt(2) lgkmcnt(0)
	v_mul_f32_e32 v115, v185, v116
	v_cndmask_b32_e64 v115, v115, -v115, vcc
	v_fmac_f32_e32 v115, v107, v184
	v_mov_b32_e32 v114, v220
	v_cndmask_b32_e64 v107, v107, v115, s[14:15]
	v_lshlrev_b32_e32 v114, 2, v114
	v_xor_b32_e32 v114, 64, v114
	ds_bpermute_b32 v116, v114, v108
	s_waitcnt vmcnt(1) lgkmcnt(0)
	v_mul_f32_e32 v115, v209, v116
	v_cndmask_b32_e64 v115, v115, -v115, vcc
	v_fmac_f32_e32 v115, v108, v208
	v_mov_b32_e32 v114, v220
	v_cndmask_b32_e64 v108, v108, v115, s[14:15]
	v_lshlrev_b32_e32 v114, 2, v114
	v_xor_b32_e32 v114, 64, v114
	ds_bpermute_b32 v116, v114, v109
	s_waitcnt vmcnt(0) lgkmcnt(0)
	v_mul_f32_e32 v115, v211, v116
	v_cndmask_b32_e64 v115, v115, -v115, vcc
	v_fmac_f32_e32 v115, v109, v210
	v_cndmask_b32_e64 v109, v109, v115, s[14:15]

;     __device__ __forceinline__ void operator()(const f32x4 (&acc)[2][2][4][2], const Unit& u, int wr, int wc, int fr, int fq) const {
;     ...
;                     if (cg0 < 384) {
;                         const float rs = RSTD[row * 2];
; #pragma unroll
;                         for (int n = 0; n < 2; ++n)
; #pragma unroll
;                             for (int j = 0; j < 4; ++j) v[4 * n + j] = acc[ai][bj][m][n][j] * rs;
;                         const int d0 = cg0 % 96;
;                         if (d0 == 64) {
;                             const bool lat = row < RL; const int t = row & 8191; const int pos = (fq >> 1) ? (t & 63) : (t >> 6); const bool isx2 = fq & 1;
; #pragma unroll
;                             for (int e = 0; e < 8; ++e) {
;                                 const float pr = shflx(v[e], 16);
;                                 const float2 cs = RT[pos * 8 + e];
;                                 const float r = isx2 ? (pr * cs.y + v[e] * cs.x) : (v[e] * cs.x - pr * cs.y);
;                                 v[e] = lat ? r : v[e];
;                             }
;                         }
.LBB0_341:
	s_andn2_saveexec_b64 s[2:3], s[0:1]
	s_cbranch_execz .LBB0_345
	global_load_dword v106, v[114:115], off
	s_waitcnt vmcnt(0)
	v_pk_mul_f32 v[102:103], v[102:103], v[106:107] op_sel_hi:[1,0]
	v_pk_mul_f32 v[104:105], v[104:105], v[106:107] op_sel_hi:[1,0]
	v_pk_mul_f32 v[98:99], v[98:99], v[106:107] op_sel_hi:[1,0]
	v_pk_mul_f32 v[100:101], v[100:101], v[106:107] op_sel_hi:[1,0]
	s_and_saveexec_b64 s[0:1], s[10:11]
	s_xor_b64 s[0:1], exec, s[0:1]
	s_andn2_saveexec_b64 s[36:37], s[0:1]
	s_cbranch_execz .LBB0_344
	v_mov_b32_e32 v107, v220
	v_cndmask_b32_e64 v106, v153, v158, s[6:7]
	v_lshlrev_b32_e32 v107, 2, v107
	v_xor_b32_e32 v107, 64, v107
	v_lshlrev_b32_e32 v109, 6, v106
	ds_bpermute_b32 v108, v107, v102
	global_load_dwordx2 v[174:175], v109, s[26:27]
	global_load_dwordx2 v[176:177], v109, s[26:27] offset:8
	global_load_dwordx2 v[178:179], v109, s[26:27] offset:16
	global_load_dwordx2 v[180:181], v109, s[26:27] offset:24
	global_load_dwordx2 v[182:183], v109, s[26:27] offset:32
	global_load_dwordx2 v[184:185], v109, s[26:27] offset:40
	global_load_dwordx2 v[208:209], v109, s[26:27] offset:48
	global_load_dwordx2 v[210:211], v109, s[26:27] offset:56
	v_cmp_gt_i32_e64 s[14:15], s95, v110
	s_waitcnt vmcnt(7) lgkmcnt(0)
	v_mul_f32_e32 v107, v175, v108
	v_cndmask_b32_e64 v107, v107, -v107, vcc
	v_fmac_f32_e32 v107, v102, v174
	v_mov_b32_e32 v106, v220
	v_cndmask_b32_e64 v102, v102, v107, s[14:15]
	v_lshlrev_b32_e32 v106, 2, v106
	v_xor_b32_e32 v106, 64, v106
	ds_bpermute_b32 v108, v106, v103
	s_waitcnt vmcnt(6) lgkmcnt(0)
	v_mul_f32_e32 v107, v177, v108
	v_cndmask_b32_e64 v107, v107, -v107, vcc
	v_fmac_f32_e32 v107, v103, v176
	v_mov_b32_e32 v106, v220
	v_cndmask_b32_e64 v103, v103, v107, s[14:15]
	v_lshlrev_b32_e32 v106, 2, v106
	v_xor_b32_e32 v106, 64, v106
	ds_bpermute_b32 v108, v106, v104
	s_waitcnt vmcnt(5) lgkmcnt(0)
	v_mul_f32_e32 v107, v179, v108
	v_cndmask_b32_e64 v107, v107, -v107, vcc
	v_fmac_f32_e32 v107, v104, v178
	v_mov_b32_e32 v106, v220
	v_cndmask_b32_e64 v104, v104, v107, s[14:15]
	v_lshlrev_b32_e32 v106, 2, v106
	v_xor_b32_e32 v106, 64, v106
	ds_bpermute_b32 v108, v106, v105
	s_waitcnt vmcnt(4) lgkmcnt(0)
	v_mul_f32_e32 v107, v181, v108
	v_cndmask_b32_e64 v107, v107, -v107, vcc
	v_fmac_f32_e32 v107, v105, v180
	v_mov_b32_e32 v106, v220
	v_cndmask_b32_e64 v105, v105, v107, s[14:15]
	v_lshlrev_b32_e32 v106, 2, v106
	v_xor_b32_e32 v106, 64, v106
	ds_bpermute_b32 v108, v106, v98
	s_waitcnt vmcnt(3) lgkmcnt(0)
	v_mul_f32_e32 v107, v183, v108
	v_cndmask_b32_e64 v107, v107, -v107, vcc
	v_fmac_f32_e32 v107, v98, v182
	v_mov_b32_e32 v106, v220
	v_cndmask_b32_e64 v98, v98, v107, s[14:15]
	v_lshlrev_b32_e32 v106, 2, v106
	v_xor_b32_e32 v106, 64, v106
	ds_bpermute_b32 v108, v106, v99
	s_waitcnt vmcnt(2) lgkmcnt(0)
	v_mul_f32_e32 v107, v185, v108
	v_cndmask_b32_e64 v107, v107, -v107, vcc
	v_fmac_f32_e32 v107, v99, v184
	v_mov_b32_e32 v106, v220
	v_cndmask_b32_e64 v99, v99, v107, s[14:15]
	v_lshlrev_b32_e32 v106, 2, v106
	v_xor_b32_e32 v106, 64, v106
	ds_bpermute_b32 v108, v106, v100
	s_waitcnt vmcnt(1) lgkmcnt(0)
	v_mul_f32_e32 v107, v209, v108
	v_cndmask_b32_e64 v107, v107, -v107, vcc
	v_fmac_f32_e32 v107, v100, v208
	v_mov_b32_e32 v106, v220
	v_cndmask_b32_e64 v100, v100, v107, s[14:15]
	v_lshlrev_b32_e32 v106, 2, v106
	v_xor_b32_e32 v106, 64, v106
	ds_bpermute_b32 v108, v106, v101
	s_waitcnt vmcnt(0) lgkmcnt(0)
	v_mul_f32_e32 v107, v211, v108
	v_cndmask_b32_e64 v107, v107, -v107, vcc
	v_fmac_f32_e32 v107, v101, v210
	v_cndmask_b32_e64 v101, v101, v107, s[14:15]

;     __device__ __forceinline__ void operator()(const f32x4 (&acc)[2][2][4][2], const Unit& u, int wr, int wc, int fr, int fq) const {
;     ...
;                     if (cg0 < 384) {
;                         const float rs = RSTD[row * 2];
; #pragma unroll
;                         for (int n = 0; n < 2; ++n)
; #pragma unroll
;                             for (int j = 0; j < 4; ++j) v[4 * n + j] = acc[ai][bj][m][n][j] * rs;
;                         const int d0 = cg0 % 96;
;                         if (d0 == 64) {
;                             const bool lat = row < RL; const int t = row & 8191; const int pos = (fq >> 1) ? (t & 63) : (t >> 6); const bool isx2 = fq & 1;
; #pragma unroll
;                             for (int e = 0; e < 8; ++e) {
;                                 const float pr = shflx(v[e], 16);
;                                 const float2 cs = RT[pos * 8 + e];
;                                 const float r = isx2 ? (pr * cs.y + v[e] * cs.x) : (v[e] * cs.x - pr * cs.y);
;                                 v[e] = lat ? r : v[e];
;                             }
;                         }
.LBB0_351:
	s_or_saveexec_b64 s[2:3], s[0:1]
	v_bfe_u32 v103, v102, 6, 7
	s_xor_b64 exec, exec, s[2:3]
	s_cbranch_execz .LBB0_355
	global_load_dword v98, v[106:107], off
	s_waitcnt vmcnt(0)
	v_pk_mul_f32 v[94:95], v[94:95], v[98:99] op_sel_hi:[1,0]
	v_pk_mul_f32 v[96:97], v[96:97], v[98:99] op_sel_hi:[1,0]
	v_pk_mul_f32 v[90:91], v[90:91], v[98:99] op_sel_hi:[1,0]
	v_pk_mul_f32 v[92:93], v[92:93], v[98:99] op_sel_hi:[1,0]
	s_and_saveexec_b64 s[0:1], s[10:11]
	s_xor_b64 s[0:1], exec, s[0:1]
	s_andn2_saveexec_b64 s[36:37], s[0:1]
	s_cbranch_execz .LBB0_354
	v_mov_b32_e32 v99, v220
	v_cndmask_b32_e64 v98, v157, v103, s[6:7]
	v_lshlrev_b32_e32 v99, 2, v99
	v_xor_b32_e32 v99, 64, v99
	v_lshlrev_b32_e32 v101, 6, v98
	ds_bpermute_b32 v100, v99, v94
	global_load_dwordx2 v[174:175], v101, s[26:27]
	global_load_dwordx2 v[176:177], v101, s[26:27] offset:8
	global_load_dwordx2 v[178:179], v101, s[26:27] offset:16
	global_load_dwordx2 v[180:181], v101, s[26:27] offset:24
	global_load_dwordx2 v[182:183], v101, s[26:27] offset:32
	global_load_dwordx2 v[184:185], v101, s[26:27] offset:40
	global_load_dwordx2 v[208:209], v101, s[26:27] offset:48
	global_load_dwordx2 v[210:211], v101, s[26:27] offset:56
	s_movk_i32 s0, 0x7f80
	v_cmp_gt_i32_e64 s[14:15], s0, v144
	s_waitcnt vmcnt(7) lgkmcnt(0)
	v_mul_f32_e32 v99, v175, v100
	v_cndmask_b32_e64 v99, v99, -v99, vcc
	v_fmac_f32_e32 v99, v94, v174
	v_mov_b32_e32 v98, v220
	v_cndmask_b32_e64 v94, v94, v99, s[14:15]
	v_lshlrev_b32_e32 v98, 2, v98
	v_xor_b32_e32 v98, 64, v98
	ds_bpermute_b32 v100, v98, v95
	s_waitcnt vmcnt(6) lgkmcnt(0)
	v_mul_f32_e32 v99, v177, v100
	v_cndmask_b32_e64 v99, v99, -v99, vcc
	v_fmac_f32_e32 v99, v95, v176
	v_mov_b32_e32 v98, v220
	v_cndmask_b32_e64 v95, v95, v99, s[14:15]
	v_lshlrev_b32_e32 v98, 2, v98
	v_xor_b32_e32 v98, 64, v98
	ds_bpermute_b32 v100, v98, v96
	s_waitcnt vmcnt(5) lgkmcnt(0)
	v_mul_f32_e32 v99, v179, v100
	v_cndmask_b32_e64 v99, v99, -v99, vcc
	v_fmac_f32_e32 v99, v96, v178
	v_mov_b32_e32 v98, v220
	v_cndmask_b32_e64 v96, v96, v99, s[14:15]
	v_lshlrev_b32_e32 v98, 2, v98
	v_xor_b32_e32 v98, 64, v98
	ds_bpermute_b32 v100, v98, v97
	s_waitcnt vmcnt(4) lgkmcnt(0)
	v_mul_f32_e32 v99, v181, v100
	v_cndmask_b32_e64 v99, v99, -v99, vcc
	v_fmac_f32_e32 v99, v97, v180
	v_mov_b32_e32 v98, v220
	v_cndmask_b32_e64 v97, v97, v99, s[14:15]
	v_lshlrev_b32_e32 v98, 2, v98
	v_xor_b32_e32 v98, 64, v98
	ds_bpermute_b32 v100, v98, v90
	s_waitcnt vmcnt(3) lgkmcnt(0)
	v_mul_f32_e32 v99, v183, v100
	v_cndmask_b32_e64 v99, v99, -v99, vcc
	v_fmac_f32_e32 v99, v90, v182
	v_mov_b32_e32 v98, v220
	v_cndmask_b32_e64 v90, v90, v99, s[14:15]
	v_lshlrev_b32_e32 v98, 2, v98
	v_xor_b32_e32 v98, 64, v98
	ds_bpermute_b32 v100, v98, v91
	s_waitcnt vmcnt(2) lgkmcnt(0)
	v_mul_f32_e32 v99, v185, v100
	v_cndmask_b32_e64 v99, v99, -v99, vcc
	v_fmac_f32_e32 v99, v91, v184
	v_mov_b32_e32 v98, v220
	v_cndmask_b32_e64 v91, v91, v99, s[14:15]
	v_lshlrev_b32_e32 v98, 2, v98
	v_xor_b32_e32 v98, 64, v98
	ds_bpermute_b32 v100, v98, v92
	s_waitcnt vmcnt(1) lgkmcnt(0)
	v_mul_f32_e32 v99, v209, v100
	v_cndmask_b32_e64 v99, v99, -v99, vcc
	v_fmac_f32_e32 v99, v92, v208
	v_mov_b32_e32 v98, v220
	v_cndmask_b32_e64 v92, v92, v99, s[14:15]
	v_lshlrev_b32_e32 v98, 2, v98
	v_xor_b32_e32 v98, 64, v98
	ds_bpermute_b32 v100, v98, v93
	s_waitcnt vmcnt(0) lgkmcnt(0)
	v_mul_f32_e32 v99, v211, v100
	v_cndmask_b32_e64 v99, v99, -v99, vcc
	v_fmac_f32_e32 v99, v93, v210
	v_cndmask_b32_e64 v93, v93, v99, s[14:15]

;     __device__ __forceinline__ void operator()(const f32x4 (&acc)[2][2][4][2], const Unit& u, int wr, int wc, int fr, int fq) const {
;     ...
;                     if (cg0 < 384) {
;                         const float rs = RSTD[row * 2];
; #pragma unroll
;                         for (int n = 0; n < 2; ++n)
; #pragma unroll
;                             for (int j = 0; j < 4; ++j) v[4 * n + j] = acc[ai][bj][m][n][j] * rs;
;                         const int d0 = cg0 % 96;
;                         if (d0 == 64) {
;                             const bool lat = row < RL; const int t = row & 8191; const int pos = (fq >> 1) ? (t & 63) : (t >> 6); const bool isx2 = fq & 1;
; #pragma unroll
;                             for (int e = 0; e < 8; ++e) {
;                                 const float pr = shflx(v[e], 16);
;                                 const float2 cs = RT[pos * 8 + e];
;                                 const float r = isx2 ? (pr * cs.y + v[e] * cs.x) : (v[e] * cs.x - pr * cs.y);
;                                 v[e] = lat ? r : v[e];
;                             }
;                         }
.LBB0_361:
	s_andn2_saveexec_b64 s[2:3], s[0:1]
	s_cbranch_execz .LBB0_365
	global_load_dword v90, v[98:99], off
	s_waitcnt vmcnt(0)
	v_pk_mul_f32 v[86:87], v[86:87], v[90:91] op_sel_hi:[1,0]
	v_pk_mul_f32 v[88:89], v[88:89], v[90:91] op_sel_hi:[1,0]
	v_pk_mul_f32 v[82:83], v[82:83], v[90:91] op_sel_hi:[1,0]
	v_pk_mul_f32 v[84:85], v[84:85], v[90:91] op_sel_hi:[1,0]
	s_and_saveexec_b64 s[0:1], s[10:11]
	s_xor_b64 s[0:1], exec, s[0:1]
	s_andn2_saveexec_b64 s[36:37], s[0:1]
	s_cbranch_execz .LBB0_364
	v_mov_b32_e32 v91, v220
	v_cndmask_b32_e64 v90, v156, v103, s[6:7]
	v_lshlrev_b32_e32 v91, 2, v91
	v_xor_b32_e32 v91, 64, v91
	v_lshlrev_b32_e32 v93, 6, v90
	ds_bpermute_b32 v92, v91, v86
	global_load_dwordx2 v[174:175], v93, s[26:27]
	global_load_dwordx2 v[176:177], v93, s[26:27] offset:8
	global_load_dwordx2 v[178:179], v93, s[26:27] offset:16
	global_load_dwordx2 v[180:181], v93, s[26:27] offset:24
	global_load_dwordx2 v[182:183], v93, s[26:27] offset:32
	global_load_dwordx2 v[184:185], v93, s[26:27] offset:40
	global_load_dwordx2 v[208:209], v93, s[26:27] offset:48
	global_load_dwordx2 v[210:211], v93, s[26:27] offset:56
	s_movk_i32 s0, 0x7f70
	v_cmp_gt_i32_e64 s[14:15], s0, v144
	s_waitcnt vmcnt(7) lgkmcnt(0)
	v_mul_f32_e32 v91, v175, v92
	v_cndmask_b32_e64 v91, v91, -v91, vcc
	v_fmac_f32_e32 v91, v86, v174
	v_mov_b32_e32 v90, v220
	v_cndmask_b32_e64 v86, v86, v91, s[14:15]
	v_lshlrev_b32_e32 v90, 2, v90
	v_xor_b32_e32 v90, 64, v90
	ds_bpermute_b32 v92, v90, v87
	s_waitcnt vmcnt(6) lgkmcnt(0)
	v_mul_f32_e32 v91, v177, v92
	v_cndmask_b32_e64 v91, v91, -v91, vcc
	v_fmac_f32_e32 v91, v87, v176
	v_mov_b32_e32 v90, v220
	v_cndmask_b32_e64 v87, v87, v91, s[14:15]
	v_lshlrev_b32_e32 v90, 2, v90
	v_xor_b32_e32 v90, 64, v90
	ds_bpermute_b32 v92, v90, v88
	s_waitcnt vmcnt(5) lgkmcnt(0)
	v_mul_f32_e32 v91, v179, v92
	v_cndmask_b32_e64 v91, v91, -v91, vcc
	v_fmac_f32_e32 v91, v88, v178
	v_mov_b32_e32 v90, v220
	v_cndmask_b32_e64 v88, v88, v91, s[14:15]
	v_lshlrev_b32_e32 v90, 2, v90
	v_xor_b32_e32 v90, 64, v90
	ds_bpermute_b32 v92, v90, v89
	s_waitcnt vmcnt(4) lgkmcnt(0)
	v_mul_f32_e32 v91, v181, v92
	v_cndmask_b32_e64 v91, v91, -v91, vcc
	v_fmac_f32_e32 v91, v89, v180
	v_mov_b32_e32 v90, v220
	v_cndmask_b32_e64 v89, v89, v91, s[14:15]
	v_lshlrev_b32_e32 v90, 2, v90
	v_xor_b32_e32 v90, 64, v90
	ds_bpermute_b32 v92, v90, v82
	s_waitcnt vmcnt(3) lgkmcnt(0)
	v_mul_f32_e32 v91, v183, v92
	v_cndmask_b32_e64 v91, v91, -v91, vcc
	v_fmac_f32_e32 v91, v82, v182
	v_mov_b32_e32 v90, v220
	v_cndmask_b32_e64 v82, v82, v91, s[14:15]
	v_lshlrev_b32_e32 v90, 2, v90
	v_xor_b32_e32 v90, 64, v90
	ds_bpermute_b32 v92, v90, v83
	s_waitcnt vmcnt(2) lgkmcnt(0)
	v_mul_f32_e32 v91, v185, v92
	v_cndmask_b32_e64 v91, v91, -v91, vcc
	v_fmac_f32_e32 v91, v83, v184
	v_mov_b32_e32 v90, v220
	v_cndmask_b32_e64 v83, v83, v91, s[14:15]
	v_lshlrev_b32_e32 v90, 2, v90
	v_xor_b32_e32 v90, 64, v90
	ds_bpermute_b32 v92, v90, v84
	s_waitcnt vmcnt(1) lgkmcnt(0)
	v_mul_f32_e32 v91, v209, v92
	v_cndmask_b32_e64 v91, v91, -v91, vcc
	v_fmac_f32_e32 v91, v84, v208
	v_mov_b32_e32 v90, v220
	v_cndmask_b32_e64 v84, v84, v91, s[14:15]
	v_lshlrev_b32_e32 v90, 2, v90
	v_xor_b32_e32 v90, 64, v90
	ds_bpermute_b32 v92, v90, v85
	s_waitcnt vmcnt(0) lgkmcnt(0)
	v_mul_f32_e32 v91, v211, v92
	v_cndmask_b32_e64 v91, v91, -v91, vcc
	v_fmac_f32_e32 v91, v85, v210
	v_cndmask_b32_e64 v85, v85, v91, s[14:15]

;     __device__ __forceinline__ void operator()(const f32x4 (&acc)[2][2][4][2], const Unit& u, int wr, int wc, int fr, int fq) const {
;     ...
;                     if (cg0 < 384) {
;                         const float rs = RSTD[row * 2];
; #pragma unroll
;                         for (int n = 0; n < 2; ++n)
; #pragma unroll
;                             for (int j = 0; j < 4; ++j) v[4 * n + j] = acc[ai][bj][m][n][j] * rs;
;                         const int d0 = cg0 % 96;
;                         if (d0 == 64) {
;                             const bool lat = row < RL; const int t = row & 8191; const int pos = (fq >> 1) ? (t & 63) : (t >> 6); const bool isx2 = fq & 1;
; #pragma unroll
;                             for (int e = 0; e < 8; ++e) {
;                                 const float pr = shflx(v[e], 16);
;                                 const float2 cs = RT[pos * 8 + e];
;                                 const float r = isx2 ? (pr * cs.y + v[e] * cs.x) : (v[e] * cs.x - pr * cs.y);
;                                 v[e] = lat ? r : v[e];
;                             }
;                         }
.LBB0_371:
	s_andn2_saveexec_b64 s[2:3], s[0:1]
	s_cbranch_execz .LBB0_375
	global_load_dword v82, v[90:91], off
	s_waitcnt vmcnt(0)
	v_pk_mul_f32 v[78:79], v[78:79], v[82:83] op_sel_hi:[1,0]
	v_pk_mul_f32 v[80:81], v[80:81], v[82:83] op_sel_hi:[1,0]
	v_pk_mul_f32 v[74:75], v[74:75], v[82:83] op_sel_hi:[1,0]
	v_pk_mul_f32 v[76:77], v[76:77], v[82:83] op_sel_hi:[1,0]
	s_and_saveexec_b64 s[0:1], s[10:11]
	s_xor_b64 s[0:1], exec, s[0:1]
	s_andn2_saveexec_b64 s[36:37], s[0:1]
	s_cbranch_execz .LBB0_374
	v_mov_b32_e32 v83, v220
	v_cndmask_b32_e64 v82, v155, v103, s[6:7]
	v_lshlrev_b32_e32 v83, 2, v83
	v_xor_b32_e32 v83, 64, v83
	v_lshlrev_b32_e32 v85, 6, v82
	ds_bpermute_b32 v84, v83, v78
	global_load_dwordx2 v[174:175], v85, s[26:27]
	global_load_dwordx2 v[176:177], v85, s[26:27] offset:8
	global_load_dwordx2 v[178:179], v85, s[26:27] offset:16
	global_load_dwordx2 v[180:181], v85, s[26:27] offset:24
	global_load_dwordx2 v[182:183], v85, s[26:27] offset:32
	global_load_dwordx2 v[184:185], v85, s[26:27] offset:40
	global_load_dwordx2 v[208:209], v85, s[26:27] offset:48
	global_load_dwordx2 v[210:211], v85, s[26:27] offset:56
	s_movk_i32 s0, 0x7f60
	v_cmp_gt_i32_e64 s[14:15], s0, v144
	s_waitcnt vmcnt(7) lgkmcnt(0)
	v_mul_f32_e32 v83, v175, v84
	v_cndmask_b32_e64 v83, v83, -v83, vcc
	v_fmac_f32_e32 v83, v78, v174
	v_mov_b32_e32 v82, v220
	v_cndmask_b32_e64 v78, v78, v83, s[14:15]
	v_lshlrev_b32_e32 v82, 2, v82
	v_xor_b32_e32 v82, 64, v82
	ds_bpermute_b32 v84, v82, v79
	s_waitcnt vmcnt(6) lgkmcnt(0)
	v_mul_f32_e32 v83, v177, v84
	v_cndmask_b32_e64 v83, v83, -v83, vcc
	v_fmac_f32_e32 v83, v79, v176
	v_mov_b32_e32 v82, v220
	v_cndmask_b32_e64 v79, v79, v83, s[14:15]
	v_lshlrev_b32_e32 v82, 2, v82
	v_xor_b32_e32 v82, 64, v82
	ds_bpermute_b32 v84, v82, v80
	s_waitcnt vmcnt(5) lgkmcnt(0)
	v_mul_f32_e32 v83, v179, v84
	v_cndmask_b32_e64 v83, v83, -v83, vcc
	v_fmac_f32_e32 v83, v80, v178
	v_mov_b32_e32 v82, v220
	v_cndmask_b32_e64 v80, v80, v83, s[14:15]
	v_lshlrev_b32_e32 v82, 2, v82
	v_xor_b32_e32 v82, 64, v82
	ds_bpermute_b32 v84, v82, v81
	s_waitcnt vmcnt(4) lgkmcnt(0)
	v_mul_f32_e32 v83, v181, v84
	v_cndmask_b32_e64 v83, v83, -v83, vcc
	v_fmac_f32_e32 v83, v81, v180
	v_mov_b32_e32 v82, v220
	v_cndmask_b32_e64 v81, v81, v83, s[14:15]
	v_lshlrev_b32_e32 v82, 2, v82
	v_xor_b32_e32 v82, 64, v82
	ds_bpermute_b32 v84, v82, v74
	s_waitcnt vmcnt(3) lgkmcnt(0)
	v_mul_f32_e32 v83, v183, v84
	v_cndmask_b32_e64 v83, v83, -v83, vcc
	v_fmac_f32_e32 v83, v74, v182
	v_mov_b32_e32 v82, v220
	v_cndmask_b32_e64 v74, v74, v83, s[14:15]
	v_lshlrev_b32_e32 v82, 2, v82
	v_xor_b32_e32 v82, 64, v82
	ds_bpermute_b32 v84, v82, v75
	s_waitcnt vmcnt(2) lgkmcnt(0)
	v_mul_f32_e32 v83, v185, v84
	v_cndmask_b32_e64 v83, v83, -v83, vcc
	v_fmac_f32_e32 v83, v75, v184
	v_mov_b32_e32 v82, v220
	v_cndmask_b32_e64 v75, v75, v83, s[14:15]
	v_lshlrev_b32_e32 v82, 2, v82
	v_xor_b32_e32 v82, 64, v82
	ds_bpermute_b32 v84, v82, v76
	s_waitcnt vmcnt(1) lgkmcnt(0)
	v_mul_f32_e32 v83, v209, v84
	v_cndmask_b32_e64 v83, v83, -v83, vcc
	v_fmac_f32_e32 v83, v76, v208
	v_mov_b32_e32 v82, v220
	v_cndmask_b32_e64 v76, v76, v83, s[14:15]
	v_lshlrev_b32_e32 v82, 2, v82
	v_xor_b32_e32 v82, 64, v82
	ds_bpermute_b32 v84, v82, v77
	s_waitcnt vmcnt(0) lgkmcnt(0)
	v_mul_f32_e32 v83, v211, v84
	v_cndmask_b32_e64 v83, v83, -v83, vcc
	v_fmac_f32_e32 v83, v77, v210
	v_cndmask_b32_e64 v77, v77, v83, s[14:15]

;     __device__ __forceinline__ void operator()(const f32x4 (&acc)[2][2][4][2], const Unit& u, int wr, int wc, int fr, int fq) const {
;     ...
;                     if (cg0 < 384) {
;                         const float rs = RSTD[row * 2];
; #pragma unroll
;                         for (int n = 0; n < 2; ++n)
; #pragma unroll
;                             for (int j = 0; j < 4; ++j) v[4 * n + j] = acc[ai][bj][m][n][j] * rs;
;                         const int d0 = cg0 % 96;
;                         if (d0 == 64) {
;                             const bool lat = row < RL; const int t = row & 8191; const int pos = (fq >> 1) ? (t & 63) : (t >> 6); const bool isx2 = fq & 1;
; #pragma unroll
;                             for (int e = 0; e < 8; ++e) {
;                                 const float pr = shflx(v[e], 16);
;                                 const float2 cs = RT[pos * 8 + e];
;                                 const float r = isx2 ? (pr * cs.y + v[e] * cs.x) : (v[e] * cs.x - pr * cs.y);
;                                 v[e] = lat ? r : v[e];
;                             }
;                         }
.LBB0_381:
	s_or_saveexec_b64 s[2:3], s[0:1]
	v_readlane_b32 s64, v254, 51
	v_readlane_b32 s65, v254, 52
	s_xor_b64 exec, exec, s[2:3]
	s_cbranch_execz .LBB0_387
	global_load_dword v74, v[82:83], off
	s_waitcnt vmcnt(0)
	v_pk_mul_f32 v[70:71], v[70:71], v[74:75] op_sel_hi:[1,0]
	v_pk_mul_f32 v[72:73], v[72:73], v[74:75] op_sel_hi:[1,0]
	v_pk_mul_f32 v[66:67], v[66:67], v[74:75] op_sel_hi:[1,0]
	v_pk_mul_f32 v[68:69], v[68:69], v[74:75] op_sel_hi:[1,0]
	s_and_saveexec_b64 s[0:1], s[10:11]
	s_xor_b64 s[0:1], exec, s[0:1]
	s_andn2_saveexec_b64 s[12:13], s[0:1]
	s_cbranch_execz .LBB0_386
	v_mov_b32_e32 v75, v220
	v_cndmask_b32_e64 v74, v153, v103, s[6:7]
	v_lshlrev_b32_e32 v75, 2, v75
	v_xor_b32_e32 v75, 64, v75
	v_lshlrev_b32_e32 v77, 6, v74
	ds_bpermute_b32 v76, v75, v70
	global_load_dwordx2 v[174:175], v77, s[26:27]
	global_load_dwordx2 v[176:177], v77, s[26:27] offset:8
	global_load_dwordx2 v[178:179], v77, s[26:27] offset:16
	global_load_dwordx2 v[180:181], v77, s[26:27] offset:24
	global_load_dwordx2 v[182:183], v77, s[26:27] offset:32
	global_load_dwordx2 v[184:185], v77, s[26:27] offset:40
	global_load_dwordx2 v[208:209], v77, s[26:27] offset:48
	global_load_dwordx2 v[210:211], v77, s[26:27] offset:56
	s_movk_i32 s0, 0x7f50
	v_cmp_gt_i32_e64 s[10:11], s0, v144
	s_waitcnt vmcnt(7) lgkmcnt(0)
	v_mul_f32_e32 v75, v175, v76
	v_cndmask_b32_e64 v75, v75, -v75, vcc
	v_fmac_f32_e32 v75, v70, v174
	v_mov_b32_e32 v74, v220
	v_cndmask_b32_e64 v70, v70, v75, s[10:11]
	v_lshlrev_b32_e32 v74, 2, v74
	v_xor_b32_e32 v74, 64, v74
	ds_bpermute_b32 v76, v74, v71
	s_waitcnt vmcnt(6) lgkmcnt(0)
	v_mul_f32_e32 v75, v177, v76
	v_cndmask_b32_e64 v75, v75, -v75, vcc
	v_fmac_f32_e32 v75, v71, v176
	v_mov_b32_e32 v74, v220
	v_cndmask_b32_e64 v71, v71, v75, s[10:11]
	v_lshlrev_b32_e32 v74, 2, v74
	v_xor_b32_e32 v74, 64, v74
	ds_bpermute_b32 v76, v74, v72
	s_waitcnt vmcnt(5) lgkmcnt(0)
	v_mul_f32_e32 v75, v179, v76
	v_cndmask_b32_e64 v75, v75, -v75, vcc
	v_fmac_f32_e32 v75, v72, v178
	v_mov_b32_e32 v74, v220
	v_cndmask_b32_e64 v72, v72, v75, s[10:11]
	v_lshlrev_b32_e32 v74, 2, v74
	v_xor_b32_e32 v74, 64, v74
	ds_bpermute_b32 v76, v74, v73
	s_waitcnt vmcnt(4) lgkmcnt(0)
	v_mul_f32_e32 v75, v181, v76
	v_cndmask_b32_e64 v75, v75, -v75, vcc
	v_fmac_f32_e32 v75, v73, v180
	v_mov_b32_e32 v74, v220
	v_cndmask_b32_e64 v73, v73, v75, s[10:11]
	v_lshlrev_b32_e32 v74, 2, v74
	v_xor_b32_e32 v74, 64, v74
	ds_bpermute_b32 v76, v74, v66
	s_waitcnt vmcnt(3) lgkmcnt(0)
	v_mul_f32_e32 v75, v183, v76
	v_cndmask_b32_e64 v75, v75, -v75, vcc
	v_fmac_f32_e32 v75, v66, v182
	v_mov_b32_e32 v74, v220
	v_cndmask_b32_e64 v66, v66, v75, s[10:11]
	v_lshlrev_b32_e32 v74, 2, v74
	v_xor_b32_e32 v74, 64, v74
	ds_bpermute_b32 v76, v74, v67
	s_waitcnt vmcnt(2) lgkmcnt(0)
	v_mul_f32_e32 v75, v185, v76
	v_cndmask_b32_e64 v75, v75, -v75, vcc
	v_fmac_f32_e32 v75, v67, v184
	v_mov_b32_e32 v74, v220
	v_cndmask_b32_e64 v67, v67, v75, s[10:11]
	v_lshlrev_b32_e32 v74, 2, v74
	v_xor_b32_e32 v74, 64, v74
	ds_bpermute_b32 v76, v74, v68
	s_waitcnt vmcnt(1) lgkmcnt(0)
	v_mul_f32_e32 v75, v209, v76
	v_cndmask_b32_e64 v75, v75, -v75, vcc
	v_fmac_f32_e32 v75, v68, v208
	v_mov_b32_e32 v74, v220
	v_cndmask_b32_e64 v68, v68, v75, s[10:11]
	v_lshlrev_b32_e32 v74, 2, v74
	v_xor_b32_e32 v74, 64, v74
	ds_bpermute_b32 v76, v74, v69
	s_waitcnt vmcnt(0) lgkmcnt(0)
	v_mul_f32_e32 v75, v211, v76
	v_cndmask_b32_e64 v75, v75, -v75, vcc
	v_fmac_f32_e32 v75, v69, v210
	v_cndmask_b32_e64 v69, v69, v75, s[10:11]

;     __device__ __forceinline__ void operator()(const f32x4 (&acc)[2][2][4][2], const Unit& u, int wr, int wc, int fr, int fq) const {
;     ...
;                     if (cg0 < 384) {
;                         const float rs = RSTD[row * 2];
; #pragma unroll
;                         for (int n = 0; n < 2; ++n)
; #pragma unroll
;                             for (int j = 0; j < 4; ++j) v[4 * n + j] = acc[ai][bj][m][n][j] * rs;
;                         const int d0 = cg0 % 96;
;                         if (d0 == 64) {
;                             const bool lat = row < RL; const int t = row & 8191; const int pos = (fq >> 1) ? (t & 63) : (t >> 6); const bool isx2 = fq & 1;
; #pragma unroll
;                             for (int e = 0; e < 8; ++e) {
;                                 const float pr = shflx(v[e], 16);
;                                 const float2 cs = RT[pos * 8 + e];
;                                 const float r = isx2 ? (pr * cs.y + v[e] * cs.x) : (v[e] * cs.x - pr * cs.y);
;                                 v[e] = lat ? r : v[e];
;                             }
;                         }
.LBB0_395:
	s_andn2_saveexec_b64 s[2:3], s[0:1]
	s_cbranch_execz .LBB0_399
	global_load_dword v66, v[72:73], off
	s_waitcnt vmcnt(0)
	v_pk_mul_f32 v[62:63], v[62:63], v[66:67] op_sel_hi:[1,0]
	v_pk_mul_f32 v[64:65], v[64:65], v[66:67] op_sel_hi:[1,0]
	v_pk_mul_f32 v[58:59], v[58:59], v[66:67] op_sel_hi:[1,0]
	v_pk_mul_f32 v[60:61], v[60:61], v[66:67] op_sel_hi:[1,0]
	s_and_saveexec_b64 s[0:1], s[10:11]
	s_xor_b64 s[0:1], exec, s[0:1]
	s_andn2_saveexec_b64 s[36:37], s[0:1]
	s_cbranch_execz .LBB0_398
	v_mov_b32_e32 v67, v220
	v_cndmask_b32_e64 v66, v157, v158, s[6:7]
	v_lshlrev_b32_e32 v67, 2, v67
	v_xor_b32_e32 v67, 64, v67
	v_lshlrev_b32_e32 v69, 6, v66
	ds_bpermute_b32 v68, v67, v62
	global_load_dwordx2 v[174:175], v69, s[26:27]
	global_load_dwordx2 v[176:177], v69, s[26:27] offset:8
	global_load_dwordx2 v[178:179], v69, s[26:27] offset:16
	global_load_dwordx2 v[180:181], v69, s[26:27] offset:24
	global_load_dwordx2 v[182:183], v69, s[26:27] offset:32
	global_load_dwordx2 v[184:185], v69, s[26:27] offset:40
	global_load_dwordx2 v[208:209], v69, s[26:27] offset:48
	global_load_dwordx2 v[210:211], v69, s[26:27] offset:56
	v_cmp_gt_i32_e64 s[14:15], s95, v144
	s_waitcnt vmcnt(7) lgkmcnt(0)
	v_mul_f32_e32 v67, v175, v68
	v_cndmask_b32_e64 v67, v67, -v67, vcc
	v_fmac_f32_e32 v67, v62, v174
	v_mov_b32_e32 v66, v220
	v_cndmask_b32_e64 v62, v62, v67, s[14:15]
	v_lshlrev_b32_e32 v66, 2, v66
	v_xor_b32_e32 v66, 64, v66
	ds_bpermute_b32 v68, v66, v63
	s_waitcnt vmcnt(6) lgkmcnt(0)
	v_mul_f32_e32 v67, v177, v68
	v_cndmask_b32_e64 v67, v67, -v67, vcc
	v_fmac_f32_e32 v67, v63, v176
	v_mov_b32_e32 v66, v220
	v_cndmask_b32_e64 v63, v63, v67, s[14:15]
	v_lshlrev_b32_e32 v66, 2, v66
	v_xor_b32_e32 v66, 64, v66
	ds_bpermute_b32 v68, v66, v64
	s_waitcnt vmcnt(5) lgkmcnt(0)
	v_mul_f32_e32 v67, v179, v68
	v_cndmask_b32_e64 v67, v67, -v67, vcc
	v_fmac_f32_e32 v67, v64, v178
	v_mov_b32_e32 v66, v220
	v_cndmask_b32_e64 v64, v64, v67, s[14:15]
	v_lshlrev_b32_e32 v66, 2, v66
	v_xor_b32_e32 v66, 64, v66
	ds_bpermute_b32 v68, v66, v65
	s_waitcnt vmcnt(4) lgkmcnt(0)
	v_mul_f32_e32 v67, v181, v68
	v_cndmask_b32_e64 v67, v67, -v67, vcc
	v_fmac_f32_e32 v67, v65, v180
	v_mov_b32_e32 v66, v220
	v_cndmask_b32_e64 v65, v65, v67, s[14:15]
	v_lshlrev_b32_e32 v66, 2, v66
	v_xor_b32_e32 v66, 64, v66
	ds_bpermute_b32 v68, v66, v58
	s_waitcnt vmcnt(3) lgkmcnt(0)
	v_mul_f32_e32 v67, v183, v68
	v_cndmask_b32_e64 v67, v67, -v67, vcc
	v_fmac_f32_e32 v67, v58, v182
	v_mov_b32_e32 v66, v220
	v_cndmask_b32_e64 v58, v58, v67, s[14:15]
	v_lshlrev_b32_e32 v66, 2, v66
	v_xor_b32_e32 v66, 64, v66
	ds_bpermute_b32 v68, v66, v59
	s_waitcnt vmcnt(2) lgkmcnt(0)
	v_mul_f32_e32 v67, v185, v68
	v_cndmask_b32_e64 v67, v67, -v67, vcc
	v_fmac_f32_e32 v67, v59, v184
	v_mov_b32_e32 v66, v220
	v_cndmask_b32_e64 v59, v59, v67, s[14:15]
	v_lshlrev_b32_e32 v66, 2, v66
	v_xor_b32_e32 v66, 64, v66
	ds_bpermute_b32 v68, v66, v60
	s_waitcnt vmcnt(1) lgkmcnt(0)
	v_mul_f32_e32 v67, v209, v68
	v_cndmask_b32_e64 v67, v67, -v67, vcc
	v_fmac_f32_e32 v67, v60, v208
	v_mov_b32_e32 v66, v220
	v_cndmask_b32_e64 v60, v60, v67, s[14:15]
	v_lshlrev_b32_e32 v66, 2, v66
	v_xor_b32_e32 v66, 64, v66
	ds_bpermute_b32 v68, v66, v61
	s_waitcnt vmcnt(0) lgkmcnt(0)
	v_mul_f32_e32 v67, v211, v68
	v_cndmask_b32_e64 v67, v67, -v67, vcc
	v_fmac_f32_e32 v67, v61, v210
	v_cndmask_b32_e64 v61, v61, v67, s[14:15]

;     __device__ __forceinline__ void operator()(const f32x4 (&acc)[2][2][4][2], const Unit& u, int wr, int wc, int fr, int fq) const {
;     ...
;                     if (cg0 < 384) {
;                         const float rs = RSTD[row * 2];
; #pragma unroll
;                         for (int n = 0; n < 2; ++n)
; #pragma unroll
;                             for (int j = 0; j < 4; ++j) v[4 * n + j] = acc[ai][bj][m][n][j] * rs;
;                         const int d0 = cg0 % 96;
;                         if (d0 == 64) {
;                             const bool lat = row < RL; const int t = row & 8191; const int pos = (fq >> 1) ? (t & 63) : (t >> 6); const bool isx2 = fq & 1;
; #pragma unroll
;                             for (int e = 0; e < 8; ++e) {
;                                 const float pr = shflx(v[e], 16);
;                                 const float2 cs = RT[pos * 8 + e];
;                                 const float r = isx2 ? (pr * cs.y + v[e] * cs.x) : (v[e] * cs.x - pr * cs.y);
;                                 v[e] = lat ? r : v[e];
;                             }
;                         }
.LBB0_405:
	s_andn2_saveexec_b64 s[2:3], s[0:1]
	s_cbranch_execz .LBB0_409
	global_load_dword v58, v[68:69], off
	s_waitcnt vmcnt(0)
	v_pk_mul_f32 v[54:55], v[54:55], v[58:59] op_sel_hi:[1,0]
	v_pk_mul_f32 v[56:57], v[56:57], v[58:59] op_sel_hi:[1,0]
	v_pk_mul_f32 v[50:51], v[50:51], v[58:59] op_sel_hi:[1,0]
	v_pk_mul_f32 v[52:53], v[52:53], v[58:59] op_sel_hi:[1,0]
	s_and_saveexec_b64 s[0:1], s[10:11]
	s_xor_b64 s[0:1], exec, s[0:1]
	s_andn2_saveexec_b64 s[36:37], s[0:1]
	s_cbranch_execz .LBB0_408
	v_mov_b32_e32 v59, v220
	v_cndmask_b32_e64 v58, v156, v158, s[6:7]
	v_lshlrev_b32_e32 v59, 2, v59
	v_xor_b32_e32 v59, 64, v59
	v_lshlrev_b32_e32 v61, 6, v58
	ds_bpermute_b32 v60, v59, v54
	global_load_dwordx2 v[174:175], v61, s[26:27]
	global_load_dwordx2 v[176:177], v61, s[26:27] offset:8
	global_load_dwordx2 v[178:179], v61, s[26:27] offset:16
	global_load_dwordx2 v[180:181], v61, s[26:27] offset:24
	global_load_dwordx2 v[182:183], v61, s[26:27] offset:32
	global_load_dwordx2 v[184:185], v61, s[26:27] offset:40
	global_load_dwordx2 v[208:209], v61, s[26:27] offset:48
	global_load_dwordx2 v[210:211], v61, s[26:27] offset:56
	v_cmp_gt_i32_e64 s[14:15], s95, v64
	s_waitcnt vmcnt(7) lgkmcnt(0)
	v_mul_f32_e32 v59, v175, v60
	v_cndmask_b32_e64 v59, v59, -v59, vcc
	v_fmac_f32_e32 v59, v54, v174
	v_mov_b32_e32 v58, v220
	v_cndmask_b32_e64 v54, v54, v59, s[14:15]
	v_lshlrev_b32_e32 v58, 2, v58
	v_xor_b32_e32 v58, 64, v58
	ds_bpermute_b32 v60, v58, v55
	s_waitcnt vmcnt(6) lgkmcnt(0)
	v_mul_f32_e32 v59, v177, v60
	v_cndmask_b32_e64 v59, v59, -v59, vcc
	v_fmac_f32_e32 v59, v55, v176
	v_mov_b32_e32 v58, v220
	v_cndmask_b32_e64 v55, v55, v59, s[14:15]
	v_lshlrev_b32_e32 v58, 2, v58
	v_xor_b32_e32 v58, 64, v58
	ds_bpermute_b32 v60, v58, v56
	s_waitcnt vmcnt(5) lgkmcnt(0)
	v_mul_f32_e32 v59, v179, v60
	v_cndmask_b32_e64 v59, v59, -v59, vcc
	v_fmac_f32_e32 v59, v56, v178
	v_mov_b32_e32 v58, v220
	v_cndmask_b32_e64 v56, v56, v59, s[14:15]
	v_lshlrev_b32_e32 v58, 2, v58
	v_xor_b32_e32 v58, 64, v58
	ds_bpermute_b32 v60, v58, v57
	s_waitcnt vmcnt(4) lgkmcnt(0)
	v_mul_f32_e32 v59, v181, v60
	v_cndmask_b32_e64 v59, v59, -v59, vcc
	v_fmac_f32_e32 v59, v57, v180
	v_mov_b32_e32 v58, v220
	v_cndmask_b32_e64 v57, v57, v59, s[14:15]
	v_lshlrev_b32_e32 v58, 2, v58
	v_xor_b32_e32 v58, 64, v58
	ds_bpermute_b32 v60, v58, v50
	s_waitcnt vmcnt(3) lgkmcnt(0)
	v_mul_f32_e32 v59, v183, v60
	v_cndmask_b32_e64 v59, v59, -v59, vcc
	v_fmac_f32_e32 v59, v50, v182
	v_mov_b32_e32 v58, v220
	v_cndmask_b32_e64 v50, v50, v59, s[14:15]
	v_lshlrev_b32_e32 v58, 2, v58
	v_xor_b32_e32 v58, 64, v58
	ds_bpermute_b32 v60, v58, v51
	s_waitcnt vmcnt(2) lgkmcnt(0)
	v_mul_f32_e32 v59, v185, v60
	v_cndmask_b32_e64 v59, v59, -v59, vcc
	v_fmac_f32_e32 v59, v51, v184
	v_mov_b32_e32 v58, v220
	v_cndmask_b32_e64 v51, v51, v59, s[14:15]
	v_lshlrev_b32_e32 v58, 2, v58
	v_xor_b32_e32 v58, 64, v58
	ds_bpermute_b32 v60, v58, v52
	s_waitcnt vmcnt(1) lgkmcnt(0)
	v_mul_f32_e32 v59, v209, v60
	v_cndmask_b32_e64 v59, v59, -v59, vcc
	v_fmac_f32_e32 v59, v52, v208
	v_mov_b32_e32 v58, v220
	v_cndmask_b32_e64 v52, v52, v59, s[14:15]
	v_lshlrev_b32_e32 v58, 2, v58
	v_xor_b32_e32 v58, 64, v58
	ds_bpermute_b32 v60, v58, v53
	s_waitcnt vmcnt(0) lgkmcnt(0)
	v_mul_f32_e32 v59, v211, v60
	v_cndmask_b32_e64 v59, v59, -v59, vcc
	v_fmac_f32_e32 v59, v53, v210
	v_cndmask_b32_e64 v53, v53, v59, s[14:15]

;     __device__ __forceinline__ void operator()(const f32x4 (&acc)[2][2][4][2], const Unit& u, int wr, int wc, int fr, int fq) const {
;     ...
;                     if (cg0 < 384) {
;                         const float rs = RSTD[row * 2];
; #pragma unroll
;                         for (int n = 0; n < 2; ++n)
; #pragma unroll
;                             for (int j = 0; j < 4; ++j) v[4 * n + j] = acc[ai][bj][m][n][j] * rs;
;                         const int d0 = cg0 % 96;
;                         if (d0 == 64) {
;                             const bool lat = row < RL; const int t = row & 8191; const int pos = (fq >> 1) ? (t & 63) : (t >> 6); const bool isx2 = fq & 1;
; #pragma unroll
;                             for (int e = 0; e < 8; ++e) {
;                                 const float pr = shflx(v[e], 16);
;                                 const float2 cs = RT[pos * 8 + e];
;                                 const float r = isx2 ? (pr * cs.y + v[e] * cs.x) : (v[e] * cs.x - pr * cs.y);
;                                 v[e] = lat ? r : v[e];
;                             }
;                         }
.LBB0_415:
	s_andn2_saveexec_b64 s[2:3], s[0:1]
	s_cbranch_execz .LBB0_419
	global_load_dword v50, v[58:59], off
	s_waitcnt vmcnt(0)
	v_pk_mul_f32 v[46:47], v[46:47], v[50:51] op_sel_hi:[1,0]
	v_pk_mul_f32 v[48:49], v[48:49], v[50:51] op_sel_hi:[1,0]
	v_pk_mul_f32 v[42:43], v[42:43], v[50:51] op_sel_hi:[1,0]
	v_pk_mul_f32 v[44:45], v[44:45], v[50:51] op_sel_hi:[1,0]
	s_and_saveexec_b64 s[0:1], s[10:11]
	s_xor_b64 s[0:1], exec, s[0:1]
	s_andn2_saveexec_b64 s[36:37], s[0:1]
	s_cbranch_execz .LBB0_418
	v_mov_b32_e32 v51, v220
	v_cndmask_b32_e64 v50, v155, v158, s[6:7]
	v_lshlrev_b32_e32 v51, 2, v51
	v_xor_b32_e32 v51, 64, v51
	v_lshlrev_b32_e32 v53, 6, v50
	ds_bpermute_b32 v52, v51, v46
	global_load_dwordx2 v[174:175], v53, s[26:27]
	global_load_dwordx2 v[176:177], v53, s[26:27] offset:8
	global_load_dwordx2 v[178:179], v53, s[26:27] offset:16
	global_load_dwordx2 v[180:181], v53, s[26:27] offset:24
	global_load_dwordx2 v[182:183], v53, s[26:27] offset:32
	global_load_dwordx2 v[184:185], v53, s[26:27] offset:40
	global_load_dwordx2 v[208:209], v53, s[26:27] offset:48
	global_load_dwordx2 v[210:211], v53, s[26:27] offset:56
	v_cmp_gt_i32_e64 s[14:15], s95, v54
	s_waitcnt vmcnt(7) lgkmcnt(0)
	v_mul_f32_e32 v51, v175, v52
	v_cndmask_b32_e64 v51, v51, -v51, vcc
	v_fmac_f32_e32 v51, v46, v174
	v_mov_b32_e32 v50, v220
	v_cndmask_b32_e64 v46, v46, v51, s[14:15]
	v_lshlrev_b32_e32 v50, 2, v50
	v_xor_b32_e32 v50, 64, v50
	ds_bpermute_b32 v52, v50, v47
	s_waitcnt vmcnt(6) lgkmcnt(0)
	v_mul_f32_e32 v51, v177, v52
	v_cndmask_b32_e64 v51, v51, -v51, vcc
	v_fmac_f32_e32 v51, v47, v176
	v_mov_b32_e32 v50, v220
	v_cndmask_b32_e64 v47, v47, v51, s[14:15]
	v_lshlrev_b32_e32 v50, 2, v50
	v_xor_b32_e32 v50, 64, v50
	ds_bpermute_b32 v52, v50, v48
	s_waitcnt vmcnt(5) lgkmcnt(0)
	v_mul_f32_e32 v51, v179, v52
	v_cndmask_b32_e64 v51, v51, -v51, vcc
	v_fmac_f32_e32 v51, v48, v178
	v_mov_b32_e32 v50, v220
	v_cndmask_b32_e64 v48, v48, v51, s[14:15]
	v_lshlrev_b32_e32 v50, 2, v50
	v_xor_b32_e32 v50, 64, v50
	ds_bpermute_b32 v52, v50, v49
	s_waitcnt vmcnt(4) lgkmcnt(0)
	v_mul_f32_e32 v51, v181, v52
	v_cndmask_b32_e64 v51, v51, -v51, vcc
	v_fmac_f32_e32 v51, v49, v180
	v_mov_b32_e32 v50, v220
	v_cndmask_b32_e64 v49, v49, v51, s[14:15]
	v_lshlrev_b32_e32 v50, 2, v50
	v_xor_b32_e32 v50, 64, v50
	ds_bpermute_b32 v52, v50, v42
	s_waitcnt vmcnt(3) lgkmcnt(0)
	v_mul_f32_e32 v51, v183, v52
	v_cndmask_b32_e64 v51, v51, -v51, vcc
	v_fmac_f32_e32 v51, v42, v182
	v_mov_b32_e32 v50, v220
	v_cndmask_b32_e64 v42, v42, v51, s[14:15]
	v_lshlrev_b32_e32 v50, 2, v50
	v_xor_b32_e32 v50, 64, v50
	ds_bpermute_b32 v52, v50, v43
	s_waitcnt vmcnt(2) lgkmcnt(0)
	v_mul_f32_e32 v51, v185, v52
	v_cndmask_b32_e64 v51, v51, -v51, vcc
	v_fmac_f32_e32 v51, v43, v184
	v_mov_b32_e32 v50, v220
	v_cndmask_b32_e64 v43, v43, v51, s[14:15]
	v_lshlrev_b32_e32 v50, 2, v50
	v_xor_b32_e32 v50, 64, v50
	ds_bpermute_b32 v52, v50, v44
	s_waitcnt vmcnt(1) lgkmcnt(0)
	v_mul_f32_e32 v51, v209, v52
	v_cndmask_b32_e64 v51, v51, -v51, vcc
	v_fmac_f32_e32 v51, v44, v208
	v_mov_b32_e32 v50, v220
	v_cndmask_b32_e64 v44, v44, v51, s[14:15]
	v_lshlrev_b32_e32 v50, 2, v50
	v_xor_b32_e32 v50, 64, v50
	ds_bpermute_b32 v52, v50, v45
	s_waitcnt vmcnt(0) lgkmcnt(0)
	v_mul_f32_e32 v51, v211, v52
	v_cndmask_b32_e64 v51, v51, -v51, vcc
	v_fmac_f32_e32 v51, v45, v210
	v_cndmask_b32_e64 v45, v45, v51, s[14:15]

;     __device__ __forceinline__ void operator()(const f32x4 (&acc)[2][2][4][2], const Unit& u, int wr, int wc, int fr, int fq) const {
;     ...
;                     if (cg0 < 384) {
;                         const float rs = RSTD[row * 2];
; #pragma unroll
;                         for (int n = 0; n < 2; ++n)
; #pragma unroll
;                             for (int j = 0; j < 4; ++j) v[4 * n + j] = acc[ai][bj][m][n][j] * rs;
;                         const int d0 = cg0 % 96;
;                         if (d0 == 64) {
;                             const bool lat = row < RL; const int t = row & 8191; const int pos = (fq >> 1) ? (t & 63) : (t >> 6); const bool isx2 = fq & 1;
; #pragma unroll
;                             for (int e = 0; e < 8; ++e) {
;                                 const float pr = shflx(v[e], 16);
;                                 const float2 cs = RT[pos * 8 + e];
;                                 const float r = isx2 ? (pr * cs.y + v[e] * cs.x) : (v[e] * cs.x - pr * cs.y);
;                                 v[e] = lat ? r : v[e];
;                             }
;                         }
.LBB0_425:
	s_andn2_saveexec_b64 s[2:3], s[0:1]
	s_cbranch_execz .LBB0_431
	global_load_dword v42, v[50:51], off
	s_waitcnt vmcnt(0)
	v_pk_mul_f32 v[38:39], v[38:39], v[42:43] op_sel_hi:[1,0]
	v_pk_mul_f32 v[40:41], v[40:41], v[42:43] op_sel_hi:[1,0]
	v_pk_mul_f32 v[34:35], v[34:35], v[42:43] op_sel_hi:[1,0]
	v_pk_mul_f32 v[36:37], v[36:37], v[42:43] op_sel_hi:[1,0]
	s_and_saveexec_b64 s[0:1], s[10:11]
	s_xor_b64 s[0:1], exec, s[0:1]
	s_andn2_saveexec_b64 s[36:37], s[0:1]
	s_cbranch_execz .LBB0_430
	v_mov_b32_e32 v43, v220
	v_cndmask_b32_e64 v42, v153, v158, s[6:7]
	v_lshlrev_b32_e32 v43, 2, v43
	v_xor_b32_e32 v43, 64, v43
	v_lshlrev_b32_e32 v45, 6, v42
	ds_bpermute_b32 v44, v43, v38
	global_load_dwordx2 v[174:175], v45, s[26:27]
	global_load_dwordx2 v[176:177], v45, s[26:27] offset:8
	global_load_dwordx2 v[178:179], v45, s[26:27] offset:16
	global_load_dwordx2 v[180:181], v45, s[26:27] offset:24
	global_load_dwordx2 v[182:183], v45, s[26:27] offset:32
	global_load_dwordx2 v[184:185], v45, s[26:27] offset:40
	global_load_dwordx2 v[208:209], v45, s[26:27] offset:48
	global_load_dwordx2 v[210:211], v45, s[26:27] offset:56
	v_cmp_gt_i32_e64 s[14:15], s95, v46
	s_waitcnt vmcnt(7) lgkmcnt(0)
	v_mul_f32_e32 v43, v175, v44
	v_cndmask_b32_e64 v43, v43, -v43, vcc
	v_fmac_f32_e32 v43, v38, v174
	v_mov_b32_e32 v42, v220
	v_cndmask_b32_e64 v38, v38, v43, s[14:15]
	v_lshlrev_b32_e32 v42, 2, v42
	v_xor_b32_e32 v42, 64, v42
	ds_bpermute_b32 v44, v42, v39
	s_waitcnt vmcnt(6) lgkmcnt(0)
	v_mul_f32_e32 v43, v177, v44
	v_cndmask_b32_e64 v43, v43, -v43, vcc
	v_fmac_f32_e32 v43, v39, v176
	v_mov_b32_e32 v42, v220
	v_cndmask_b32_e64 v39, v39, v43, s[14:15]
	v_lshlrev_b32_e32 v42, 2, v42
	v_xor_b32_e32 v42, 64, v42
	ds_bpermute_b32 v44, v42, v40
	s_waitcnt vmcnt(5) lgkmcnt(0)
	v_mul_f32_e32 v43, v179, v44
	v_cndmask_b32_e64 v43, v43, -v43, vcc
	v_fmac_f32_e32 v43, v40, v178
	v_mov_b32_e32 v42, v220
	v_cndmask_b32_e64 v40, v40, v43, s[14:15]
	v_lshlrev_b32_e32 v42, 2, v42
	v_xor_b32_e32 v42, 64, v42
	ds_bpermute_b32 v44, v42, v41
	s_waitcnt vmcnt(4) lgkmcnt(0)
	v_mul_f32_e32 v43, v181, v44
	v_cndmask_b32_e64 v43, v43, -v43, vcc
	v_fmac_f32_e32 v43, v41, v180
	v_mov_b32_e32 v42, v220
	v_cndmask_b32_e64 v41, v41, v43, s[14:15]
	v_lshlrev_b32_e32 v42, 2, v42
	v_xor_b32_e32 v42, 64, v42
	ds_bpermute_b32 v44, v42, v34
	s_waitcnt vmcnt(3) lgkmcnt(0)
	v_mul_f32_e32 v43, v183, v44
	v_cndmask_b32_e64 v43, v43, -v43, vcc
	v_fmac_f32_e32 v43, v34, v182
	v_mov_b32_e32 v42, v220
	v_cndmask_b32_e64 v34, v34, v43, s[14:15]
	v_lshlrev_b32_e32 v42, 2, v42
	v_xor_b32_e32 v42, 64, v42
	ds_bpermute_b32 v44, v42, v35
	s_waitcnt vmcnt(2) lgkmcnt(0)
	v_mul_f32_e32 v43, v185, v44
	v_cndmask_b32_e64 v43, v43, -v43, vcc
	v_fmac_f32_e32 v43, v35, v184
	v_mov_b32_e32 v42, v220
	v_cndmask_b32_e64 v35, v35, v43, s[14:15]
	v_lshlrev_b32_e32 v42, 2, v42
	v_xor_b32_e32 v42, 64, v42
	ds_bpermute_b32 v44, v42, v36
	s_waitcnt vmcnt(1) lgkmcnt(0)
	v_mul_f32_e32 v43, v209, v44
	v_cndmask_b32_e64 v43, v43, -v43, vcc
	v_fmac_f32_e32 v43, v36, v208
	v_mov_b32_e32 v42, v220
	v_cndmask_b32_e64 v36, v36, v43, s[14:15]
	v_lshlrev_b32_e32 v42, 2, v42
	v_xor_b32_e32 v42, 64, v42
	ds_bpermute_b32 v44, v42, v37
	s_waitcnt vmcnt(0) lgkmcnt(0)
	v_mul_f32_e32 v43, v211, v44
	v_cndmask_b32_e64 v43, v43, -v43, vcc
	v_fmac_f32_e32 v43, v37, v210
	v_cndmask_b32_e64 v37, v37, v43, s[14:15]

;     __device__ __forceinline__ void operator()(const f32x4 (&acc)[2][2][4][2], const Unit& u, int wr, int wc, int fr, int fq) const {
;     ...
;                     if (cg0 < 384) {
;                         const float rs = RSTD[row * 2];
; #pragma unroll
;                         for (int n = 0; n < 2; ++n)
; #pragma unroll
;                             for (int j = 0; j < 4; ++j) v[4 * n + j] = acc[ai][bj][m][n][j] * rs;
;                         const int d0 = cg0 % 96;
;                         if (d0 == 64) {
;                             const bool lat = row < RL; const int t = row & 8191; const int pos = (fq >> 1) ? (t & 63) : (t >> 6); const bool isx2 = fq & 1;
; #pragma unroll
;                             for (int e = 0; e < 8; ++e) {
;                                 const float pr = shflx(v[e], 16);
;                                 const float2 cs = RT[pos * 8 + e];
;                                 const float r = isx2 ? (pr * cs.y + v[e] * cs.x) : (v[e] * cs.x - pr * cs.y);
;                                 v[e] = lat ? r : v[e];
;                             }
;                         }
.LBB0_437:
	s_or_saveexec_b64 s[2:3], s[0:1]
	v_bfe_u32 v39, v38, 6, 7
	s_xor_b64 exec, exec, s[2:3]
	s_cbranch_execz .LBB0_443
	global_load_dword v34, v[42:43], off
	s_waitcnt vmcnt(0)
	v_pk_mul_f32 v[30:31], v[30:31], v[34:35] op_sel_hi:[1,0]
	v_pk_mul_f32 v[32:33], v[32:33], v[34:35] op_sel_hi:[1,0]
	v_pk_mul_f32 v[26:27], v[26:27], v[34:35] op_sel_hi:[1,0]
	v_pk_mul_f32 v[28:29], v[28:29], v[34:35] op_sel_hi:[1,0]
	s_and_saveexec_b64 s[0:1], s[10:11]
	s_xor_b64 s[0:1], exec, s[0:1]
	s_andn2_saveexec_b64 s[36:37], s[0:1]
	s_cbranch_execz .LBB0_442
	v_mov_b32_e32 v35, v220
	v_cndmask_b32_e64 v34, v157, v39, s[6:7]
	v_lshlrev_b32_e32 v35, 2, v35
	v_xor_b32_e32 v35, 64, v35
	v_lshlrev_b32_e32 v37, 6, v34
	ds_bpermute_b32 v36, v35, v30
	global_load_dwordx2 v[174:175], v37, s[26:27]
	global_load_dwordx2 v[176:177], v37, s[26:27] offset:8
	global_load_dwordx2 v[178:179], v37, s[26:27] offset:16
	global_load_dwordx2 v[180:181], v37, s[26:27] offset:24
	global_load_dwordx2 v[182:183], v37, s[26:27] offset:32
	global_load_dwordx2 v[184:185], v37, s[26:27] offset:40
	global_load_dwordx2 v[208:209], v37, s[26:27] offset:48
	global_load_dwordx2 v[210:211], v37, s[26:27] offset:56
	s_movk_i32 s0, 0x7f80
	v_cmp_gt_i32_e64 s[14:15], s0, v144
	s_waitcnt vmcnt(7) lgkmcnt(0)
	v_mul_f32_e32 v35, v175, v36
	v_cndmask_b32_e64 v35, v35, -v35, vcc
	v_fmac_f32_e32 v35, v30, v174
	v_mov_b32_e32 v34, v220
	v_cndmask_b32_e64 v30, v30, v35, s[14:15]
	v_lshlrev_b32_e32 v34, 2, v34
	v_xor_b32_e32 v34, 64, v34
	ds_bpermute_b32 v36, v34, v31
	s_waitcnt vmcnt(6) lgkmcnt(0)
	v_mul_f32_e32 v35, v177, v36
	v_cndmask_b32_e64 v35, v35, -v35, vcc
	v_fmac_f32_e32 v35, v31, v176
	v_mov_b32_e32 v34, v220
	v_cndmask_b32_e64 v31, v31, v35, s[14:15]
	v_lshlrev_b32_e32 v34, 2, v34
	v_xor_b32_e32 v34, 64, v34
	ds_bpermute_b32 v36, v34, v32
	s_waitcnt vmcnt(5) lgkmcnt(0)
	v_mul_f32_e32 v35, v179, v36
	v_cndmask_b32_e64 v35, v35, -v35, vcc
	v_fmac_f32_e32 v35, v32, v178
	v_mov_b32_e32 v34, v220
	v_cndmask_b32_e64 v32, v32, v35, s[14:15]
	v_lshlrev_b32_e32 v34, 2, v34
	v_xor_b32_e32 v34, 64, v34
	ds_bpermute_b32 v36, v34, v33
	s_waitcnt vmcnt(4) lgkmcnt(0)
	v_mul_f32_e32 v35, v181, v36
	v_cndmask_b32_e64 v35, v35, -v35, vcc
	v_fmac_f32_e32 v35, v33, v180
	v_mov_b32_e32 v34, v220
	v_cndmask_b32_e64 v33, v33, v35, s[14:15]
	v_lshlrev_b32_e32 v34, 2, v34
	v_xor_b32_e32 v34, 64, v34
	ds_bpermute_b32 v36, v34, v26
	s_waitcnt vmcnt(3) lgkmcnt(0)
	v_mul_f32_e32 v35, v183, v36
	v_cndmask_b32_e64 v35, v35, -v35, vcc
	v_fmac_f32_e32 v35, v26, v182
	v_mov_b32_e32 v34, v220
	v_cndmask_b32_e64 v26, v26, v35, s[14:15]
	v_lshlrev_b32_e32 v34, 2, v34
	v_xor_b32_e32 v34, 64, v34
	ds_bpermute_b32 v36, v34, v27
	s_waitcnt vmcnt(2) lgkmcnt(0)
	v_mul_f32_e32 v35, v185, v36
	v_cndmask_b32_e64 v35, v35, -v35, vcc
	v_fmac_f32_e32 v35, v27, v184
	v_mov_b32_e32 v34, v220
	v_cndmask_b32_e64 v27, v27, v35, s[14:15]
	v_lshlrev_b32_e32 v34, 2, v34
	v_xor_b32_e32 v34, 64, v34
	ds_bpermute_b32 v36, v34, v28
	s_waitcnt vmcnt(1) lgkmcnt(0)
	v_mul_f32_e32 v35, v209, v36
	v_cndmask_b32_e64 v35, v35, -v35, vcc
	v_fmac_f32_e32 v35, v28, v208
	v_mov_b32_e32 v34, v220
	v_cndmask_b32_e64 v28, v28, v35, s[14:15]
	v_lshlrev_b32_e32 v34, 2, v34
	v_xor_b32_e32 v34, 64, v34
	ds_bpermute_b32 v36, v34, v29
	s_waitcnt vmcnt(0) lgkmcnt(0)
	v_mul_f32_e32 v35, v211, v36
	v_cndmask_b32_e64 v35, v35, -v35, vcc
	v_fmac_f32_e32 v35, v29, v210
	v_cndmask_b32_e64 v29, v29, v35, s[14:15]

;     __device__ __forceinline__ void operator()(const f32x4 (&acc)[2][2][4][2], const Unit& u, int wr, int wc, int fr, int fq) const {
;     ...
;                     if (cg0 < 384) {
;                         const float rs = RSTD[row * 2];
; #pragma unroll
;                         for (int n = 0; n < 2; ++n)
; #pragma unroll
;                             for (int j = 0; j < 4; ++j) v[4 * n + j] = acc[ai][bj][m][n][j] * rs;
;                         const int d0 = cg0 % 96;
;                         if (d0 == 64) {
;                             const bool lat = row < RL; const int t = row & 8191; const int pos = (fq >> 1) ? (t & 63) : (t >> 6); const bool isx2 = fq & 1;
; #pragma unroll
;                             for (int e = 0; e < 8; ++e) {
;                                 const float pr = shflx(v[e], 16);
;                                 const float2 cs = RT[pos * 8 + e];
;                                 const float r = isx2 ? (pr * cs.y + v[e] * cs.x) : (v[e] * cs.x - pr * cs.y);
;                                 v[e] = lat ? r : v[e];
;                             }
;                         }
.LBB0_449:
	s_andn2_saveexec_b64 s[2:3], s[0:1]
	s_cbranch_execz .LBB0_455
	global_load_dword v26, v[34:35], off
	s_waitcnt vmcnt(0)
	v_pk_mul_f32 v[22:23], v[22:23], v[26:27] op_sel_hi:[1,0]
	v_pk_mul_f32 v[24:25], v[24:25], v[26:27] op_sel_hi:[1,0]
	v_pk_mul_f32 v[18:19], v[18:19], v[26:27] op_sel_hi:[1,0]
	v_pk_mul_f32 v[20:21], v[20:21], v[26:27] op_sel_hi:[1,0]
	s_and_saveexec_b64 s[0:1], s[10:11]
	s_xor_b64 s[0:1], exec, s[0:1]
	s_andn2_saveexec_b64 s[36:37], s[0:1]
	s_cbranch_execz .LBB0_454
	v_mov_b32_e32 v27, v220
	v_cndmask_b32_e64 v26, v156, v39, s[6:7]
	v_lshlrev_b32_e32 v27, 2, v27
	v_xor_b32_e32 v27, 64, v27
	v_lshlrev_b32_e32 v29, 6, v26
	ds_bpermute_b32 v28, v27, v22
	global_load_dwordx2 v[174:175], v29, s[26:27]
	global_load_dwordx2 v[176:177], v29, s[26:27] offset:8
	global_load_dwordx2 v[178:179], v29, s[26:27] offset:16
	global_load_dwordx2 v[180:181], v29, s[26:27] offset:24
	global_load_dwordx2 v[182:183], v29, s[26:27] offset:32
	global_load_dwordx2 v[184:185], v29, s[26:27] offset:40
	global_load_dwordx2 v[208:209], v29, s[26:27] offset:48
	global_load_dwordx2 v[210:211], v29, s[26:27] offset:56
	s_movk_i32 s0, 0x7f70
	v_cmp_gt_i32_e64 s[14:15], s0, v144
	s_waitcnt vmcnt(7) lgkmcnt(0)
	v_mul_f32_e32 v27, v175, v28
	v_cndmask_b32_e64 v27, v27, -v27, vcc
	v_fmac_f32_e32 v27, v22, v174
	v_mov_b32_e32 v26, v220
	v_cndmask_b32_e64 v22, v22, v27, s[14:15]
	v_lshlrev_b32_e32 v26, 2, v26
	v_xor_b32_e32 v26, 64, v26
	ds_bpermute_b32 v28, v26, v23
	s_waitcnt vmcnt(6) lgkmcnt(0)
	v_mul_f32_e32 v27, v177, v28
	v_cndmask_b32_e64 v27, v27, -v27, vcc
	v_fmac_f32_e32 v27, v23, v176
	v_mov_b32_e32 v26, v220
	v_cndmask_b32_e64 v23, v23, v27, s[14:15]
	v_lshlrev_b32_e32 v26, 2, v26
	v_xor_b32_e32 v26, 64, v26
	ds_bpermute_b32 v28, v26, v24
	s_waitcnt vmcnt(5) lgkmcnt(0)
	v_mul_f32_e32 v27, v179, v28
	v_cndmask_b32_e64 v27, v27, -v27, vcc
	v_fmac_f32_e32 v27, v24, v178
	v_mov_b32_e32 v26, v220
	v_cndmask_b32_e64 v24, v24, v27, s[14:15]
	v_lshlrev_b32_e32 v26, 2, v26
	v_xor_b32_e32 v26, 64, v26
	ds_bpermute_b32 v28, v26, v25
	s_waitcnt vmcnt(4) lgkmcnt(0)
	v_mul_f32_e32 v27, v181, v28
	v_cndmask_b32_e64 v27, v27, -v27, vcc
	v_fmac_f32_e32 v27, v25, v180
	v_mov_b32_e32 v26, v220
	v_cndmask_b32_e64 v25, v25, v27, s[14:15]
	v_lshlrev_b32_e32 v26, 2, v26
	v_xor_b32_e32 v26, 64, v26
	ds_bpermute_b32 v28, v26, v18
	s_waitcnt vmcnt(3) lgkmcnt(0)
	v_mul_f32_e32 v27, v183, v28
	v_cndmask_b32_e64 v27, v27, -v27, vcc
	v_fmac_f32_e32 v27, v18, v182
	v_mov_b32_e32 v26, v220
	v_cndmask_b32_e64 v18, v18, v27, s[14:15]
	v_lshlrev_b32_e32 v26, 2, v26
	v_xor_b32_e32 v26, 64, v26
	ds_bpermute_b32 v28, v26, v19
	s_waitcnt vmcnt(2) lgkmcnt(0)
	v_mul_f32_e32 v27, v185, v28
	v_cndmask_b32_e64 v27, v27, -v27, vcc
	v_fmac_f32_e32 v27, v19, v184
	v_mov_b32_e32 v26, v220
	v_cndmask_b32_e64 v19, v19, v27, s[14:15]
	v_lshlrev_b32_e32 v26, 2, v26
	v_xor_b32_e32 v26, 64, v26
	ds_bpermute_b32 v28, v26, v20
	s_waitcnt vmcnt(1) lgkmcnt(0)
	v_mul_f32_e32 v27, v209, v28
	v_cndmask_b32_e64 v27, v27, -v27, vcc
	v_fmac_f32_e32 v27, v20, v208
	v_mov_b32_e32 v26, v220
	v_cndmask_b32_e64 v20, v20, v27, s[14:15]
	v_lshlrev_b32_e32 v26, 2, v26
	v_xor_b32_e32 v26, 64, v26
	ds_bpermute_b32 v28, v26, v21
	s_waitcnt vmcnt(0) lgkmcnt(0)
	v_mul_f32_e32 v27, v211, v28
	v_cndmask_b32_e64 v27, v27, -v27, vcc
	v_fmac_f32_e32 v27, v21, v210
	v_cndmask_b32_e64 v21, v21, v27, s[14:15]

;     __device__ __forceinline__ void operator()(const f32x4 (&acc)[2][2][4][2], const Unit& u, int wr, int wc, int fr, int fq) const {
;     ...
;                     if (cg0 < 384) {
;                         const float rs = RSTD[row * 2];
; #pragma unroll
;                         for (int n = 0; n < 2; ++n)
; #pragma unroll
;                             for (int j = 0; j < 4; ++j) v[4 * n + j] = acc[ai][bj][m][n][j] * rs;
;                         const int d0 = cg0 % 96;
;                         if (d0 == 64) {
;                             const bool lat = row < RL; const int t = row & 8191; const int pos = (fq >> 1) ? (t & 63) : (t >> 6); const bool isx2 = fq & 1;
; #pragma unroll
;                             for (int e = 0; e < 8; ++e) {
;                                 const float pr = shflx(v[e], 16);
;                                 const float2 cs = RT[pos * 8 + e];
;                                 const float r = isx2 ? (pr * cs.y + v[e] * cs.x) : (v[e] * cs.x - pr * cs.y);
;                                 v[e] = lat ? r : v[e];
;                             }
;                         }
.LBB0_461:
	s_andn2_saveexec_b64 s[2:3], s[0:1]
	s_cbranch_execz .LBB0_467
	global_load_dword v18, v[26:27], off
	s_waitcnt vmcnt(0)
	v_pk_mul_f32 v[14:15], v[14:15], v[18:19] op_sel_hi:[1,0]
	v_pk_mul_f32 v[16:17], v[16:17], v[18:19] op_sel_hi:[1,0]
	v_pk_mul_f32 v[10:11], v[10:11], v[18:19] op_sel_hi:[1,0]
	v_pk_mul_f32 v[12:13], v[12:13], v[18:19] op_sel_hi:[1,0]
	s_and_saveexec_b64 s[0:1], s[10:11]
	s_xor_b64 s[0:1], exec, s[0:1]
	s_andn2_saveexec_b64 s[36:37], s[0:1]
	s_cbranch_execz .LBB0_466
	v_mov_b32_e32 v19, v220
	v_cndmask_b32_e64 v18, v155, v39, s[6:7]
	v_lshlrev_b32_e32 v19, 2, v19
	v_xor_b32_e32 v19, 64, v19
	v_lshlrev_b32_e32 v21, 6, v18
	ds_bpermute_b32 v20, v19, v14
	global_load_dwordx2 v[174:175], v21, s[26:27]
	global_load_dwordx2 v[176:177], v21, s[26:27] offset:8
	global_load_dwordx2 v[178:179], v21, s[26:27] offset:16
	global_load_dwordx2 v[180:181], v21, s[26:27] offset:24
	global_load_dwordx2 v[182:183], v21, s[26:27] offset:32
	global_load_dwordx2 v[184:185], v21, s[26:27] offset:40
	global_load_dwordx2 v[208:209], v21, s[26:27] offset:48
	global_load_dwordx2 v[210:211], v21, s[26:27] offset:56
	s_movk_i32 s0, 0x7f60
	v_cmp_gt_i32_e64 s[14:15], s0, v144
	s_waitcnt vmcnt(7) lgkmcnt(0)
	v_mul_f32_e32 v19, v175, v20
	v_cndmask_b32_e64 v19, v19, -v19, vcc
	v_fmac_f32_e32 v19, v14, v174
	v_mov_b32_e32 v18, v220
	v_cndmask_b32_e64 v14, v14, v19, s[14:15]
	v_lshlrev_b32_e32 v18, 2, v18
	v_xor_b32_e32 v18, 64, v18
	ds_bpermute_b32 v20, v18, v15
	s_waitcnt vmcnt(6) lgkmcnt(0)
	v_mul_f32_e32 v19, v177, v20
	v_cndmask_b32_e64 v19, v19, -v19, vcc
	v_fmac_f32_e32 v19, v15, v176
	v_mov_b32_e32 v18, v220
	v_cndmask_b32_e64 v15, v15, v19, s[14:15]
	v_lshlrev_b32_e32 v18, 2, v18
	v_xor_b32_e32 v18, 64, v18
	ds_bpermute_b32 v20, v18, v16
	s_waitcnt vmcnt(5) lgkmcnt(0)
	v_mul_f32_e32 v19, v179, v20
	v_cndmask_b32_e64 v19, v19, -v19, vcc
	v_fmac_f32_e32 v19, v16, v178
	v_mov_b32_e32 v18, v220
	v_cndmask_b32_e64 v16, v16, v19, s[14:15]
	v_lshlrev_b32_e32 v18, 2, v18
	v_xor_b32_e32 v18, 64, v18
	ds_bpermute_b32 v20, v18, v17
	s_waitcnt vmcnt(4) lgkmcnt(0)
	v_mul_f32_e32 v19, v181, v20
	v_cndmask_b32_e64 v19, v19, -v19, vcc
	v_fmac_f32_e32 v19, v17, v180
	v_mov_b32_e32 v18, v220
	v_cndmask_b32_e64 v17, v17, v19, s[14:15]
	v_lshlrev_b32_e32 v18, 2, v18
	v_xor_b32_e32 v18, 64, v18
	ds_bpermute_b32 v20, v18, v10
	s_waitcnt vmcnt(3) lgkmcnt(0)
	v_mul_f32_e32 v19, v183, v20
	v_cndmask_b32_e64 v19, v19, -v19, vcc
	v_fmac_f32_e32 v19, v10, v182
	v_mov_b32_e32 v18, v220
	v_cndmask_b32_e64 v10, v10, v19, s[14:15]
	v_lshlrev_b32_e32 v18, 2, v18
	v_xor_b32_e32 v18, 64, v18
	ds_bpermute_b32 v20, v18, v11
	s_waitcnt vmcnt(2) lgkmcnt(0)
	v_mul_f32_e32 v19, v185, v20
	v_cndmask_b32_e64 v19, v19, -v19, vcc
	v_fmac_f32_e32 v19, v11, v184
	v_mov_b32_e32 v18, v220
	v_cndmask_b32_e64 v11, v11, v19, s[14:15]
	v_lshlrev_b32_e32 v18, 2, v18
	v_xor_b32_e32 v18, 64, v18
	ds_bpermute_b32 v20, v18, v12
	s_waitcnt vmcnt(1) lgkmcnt(0)
	v_mul_f32_e32 v19, v209, v20
	v_cndmask_b32_e64 v19, v19, -v19, vcc
	v_fmac_f32_e32 v19, v12, v208
	v_mov_b32_e32 v18, v220
	v_cndmask_b32_e64 v12, v12, v19, s[14:15]
	v_lshlrev_b32_e32 v18, 2, v18
	v_xor_b32_e32 v18, 64, v18
	ds_bpermute_b32 v20, v18, v13
	s_waitcnt vmcnt(0) lgkmcnt(0)
	v_mul_f32_e32 v19, v211, v20
	v_cndmask_b32_e64 v19, v19, -v19, vcc
	v_fmac_f32_e32 v19, v13, v210
	v_cndmask_b32_e64 v13, v13, v19, s[14:15]

; __device__ __forceinline__ unsigned cvt_pk_bf16(float lo, float hi) { const f32x2_ v = {lo, hi}; return __builtin_bit_cast(unsigned, __builtin_convertvector(v, bf16x2_)); }
;     __device__ __forceinline__ void operator()(const f32x4 (&acc)[2][2][4][2], const Unit& u, int wr, int wc, int fr, int fq) const {
;     ...
;                     if (cg0 < 384) {
;                         const float rs = RSTD[row * 2];
; #pragma unroll
;                         for (int n = 0; n < 2; ++n)
; #pragma unroll
;                             for (int j = 0; j < 4; ++j) v[4 * n + j] = acc[ai][bj][m][n][j] * rs;
;                         const int d0 = cg0 % 96;
;                         if (d0 == 64) {
;                             const bool lat = row < RL; const int t = row & 8191; const int pos = (fq >> 1) ? (t & 63) : (t >> 6); const bool isx2 = fq & 1;
; #pragma unroll
;                             for (int e = 0; e < 8; ++e) {
;                                 const float pr = shflx(v[e], 16);
;                                 const float2 cs = RT[pos * 8 + e];
;                                 const float r = isx2 ? (pr * cs.y + v[e] * cs.x) : (v[e] * cs.x - pr * cs.y);
;                                 v[e] = lat ? r : v[e];
;                             }
;                         }
;                         u32x4 w; w.x = cvt_pk_bf16(v[0], v[1]); w.y = cvt_pk_bf16(v[2], v[3]); w.z = cvt_pk_bf16(v[4], v[5]); w.w = cvt_pk_bf16(v[6], v[7]);
;                         *(u32x4*)(MQ + (size_t)row * 384 + cg0 + 8 * fq) = w;
.LBB0_473:
	s_andn2_saveexec_b64 s[2:3], s[0:1]
	s_cbranch_execz .LBB0_296
	global_load_dword v10, v[18:19], off
	s_waitcnt vmcnt(0)
	v_pk_mul_f32 v[6:7], v[6:7], v[10:11] op_sel_hi:[1,0]
	v_pk_mul_f32 v[8:9], v[8:9], v[10:11] op_sel_hi:[1,0]
	v_pk_mul_f32 v[2:3], v[2:3], v[10:11] op_sel_hi:[1,0]
	v_pk_mul_f32 v[4:5], v[4:5], v[10:11] op_sel_hi:[1,0]
	s_and_saveexec_b64 s[0:1], s[10:11]
	s_xor_b64 s[0:1], exec, s[0:1]
	s_andn2_saveexec_b64 s[10:11], s[0:1]
	s_cbranch_execz .LBB0_295
	v_mov_b32_e32 v11, v220
	v_cndmask_b32_e64 v10, v153, v39, s[6:7]
	v_lshlrev_b32_e32 v11, 2, v11
	v_xor_b32_e32 v11, 64, v11
	v_lshlrev_b32_e32 v13, 6, v10
	ds_bpermute_b32 v12, v11, v6
	global_load_dwordx2 v[174:175], v13, s[26:27]
	global_load_dwordx2 v[176:177], v13, s[26:27] offset:8
	global_load_dwordx2 v[178:179], v13, s[26:27] offset:16
	global_load_dwordx2 v[180:181], v13, s[26:27] offset:24
	global_load_dwordx2 v[182:183], v13, s[26:27] offset:32
	global_load_dwordx2 v[184:185], v13, s[26:27] offset:40
	global_load_dwordx2 v[208:209], v13, s[26:27] offset:48
	global_load_dwordx2 v[210:211], v13, s[26:27] offset:56
	s_movk_i32 s0, 0x7f50
	v_cmp_gt_i32_e64 s[8:9], s0, v144
	s_waitcnt vmcnt(7) lgkmcnt(0)
	v_mul_f32_e32 v11, v175, v12
	v_cndmask_b32_e64 v11, v11, -v11, vcc
	v_fmac_f32_e32 v11, v6, v174
	v_mov_b32_e32 v10, v220
	v_cndmask_b32_e64 v6, v6, v11, s[8:9]
	v_lshlrev_b32_e32 v10, 2, v10
	v_xor_b32_e32 v10, 64, v10
	ds_bpermute_b32 v12, v10, v7
	s_waitcnt vmcnt(6) lgkmcnt(0)
	v_mul_f32_e32 v11, v177, v12
	v_cndmask_b32_e64 v11, v11, -v11, vcc
	v_fmac_f32_e32 v11, v7, v176
	v_mov_b32_e32 v10, v220
	v_cndmask_b32_e64 v7, v7, v11, s[8:9]
	v_lshlrev_b32_e32 v10, 2, v10
	v_xor_b32_e32 v10, 64, v10
	ds_bpermute_b32 v12, v10, v8
	s_waitcnt vmcnt(5) lgkmcnt(0)
	v_mul_f32_e32 v11, v179, v12
	v_cndmask_b32_e64 v11, v11, -v11, vcc
	v_fmac_f32_e32 v11, v8, v178
	v_mov_b32_e32 v10, v220
	v_cndmask_b32_e64 v8, v8, v11, s[8:9]
	v_lshlrev_b32_e32 v10, 2, v10
	v_xor_b32_e32 v10, 64, v10
	ds_bpermute_b32 v12, v10, v9
	s_waitcnt vmcnt(4) lgkmcnt(0)
	v_mul_f32_e32 v11, v181, v12
	v_cndmask_b32_e64 v11, v11, -v11, vcc
	v_fmac_f32_e32 v11, v9, v180
	v_mov_b32_e32 v10, v220
	v_cndmask_b32_e64 v9, v9, v11, s[8:9]
	v_lshlrev_b32_e32 v10, 2, v10
	v_xor_b32_e32 v10, 64, v10
	ds_bpermute_b32 v12, v10, v2
	s_waitcnt vmcnt(3) lgkmcnt(0)
	v_mul_f32_e32 v11, v183, v12
	v_cndmask_b32_e64 v11, v11, -v11, vcc
	v_fmac_f32_e32 v11, v2, v182
	v_mov_b32_e32 v10, v220
	v_cndmask_b32_e64 v2, v2, v11, s[8:9]
	v_lshlrev_b32_e32 v10, 2, v10
	v_xor_b32_e32 v10, 64, v10
	ds_bpermute_b32 v12, v10, v3
	s_waitcnt vmcnt(2) lgkmcnt(0)
	v_mul_f32_e32 v11, v185, v12
	v_cndmask_b32_e64 v11, v11, -v11, vcc
	v_fmac_f32_e32 v11, v3, v184
	v_mov_b32_e32 v10, v220
	v_cndmask_b32_e64 v3, v3, v11, s[8:9]
	v_lshlrev_b32_e32 v10, 2, v10
	v_xor_b32_e32 v10, 64, v10
	ds_bpermute_b32 v12, v10, v4
	s_waitcnt vmcnt(1) lgkmcnt(0)
	v_mul_f32_e32 v11, v209, v12
	v_cndmask_b32_e64 v11, v11, -v11, vcc
	v_fmac_f32_e32 v11, v4, v208
	v_mov_b32_e32 v10, v220
	v_cndmask_b32_e64 v4, v4, v11, s[8:9]
	v_lshlrev_b32_e32 v10, 2, v10
	v_xor_b32_e32 v10, 64, v10
	ds_bpermute_b32 v12, v10, v5
	s_waitcnt vmcnt(0) lgkmcnt(0)
	v_mul_f32_e32 v11, v211, v12
	v_cndmask_b32_e64 v11, v11, -v11, vcc
	v_fmac_f32_e32 v11, v5, v210
	v_cndmask_b32_e64 v5, v5, v11, s[8:9]
	s_branch .LBB0_295

;     __device__ bool next(int i, Unit& u) const { if (i > 0 || !has) return false; u.pm = pm; u.pn = pn; return true; }
; #define PG8_STAGE(bufoff, gbase, voff) do { _Pragma("unroll") for (int _i = 0; _i < 2; ++_i) \
;         __builtin_amdgcn_global_load_lds((const unsigned*)((const char*)(gbase) + (voff)[_i]), (LAS unsigned*)(lds + (bufoff) + ldsw + _i * 8192), 16, 0, 0); } while (0)
; #define PG8_WAIT_V(n) asm volatile("s_waitcnt vmcnt(" #n ")" ::: "memory")
; template <class Epi, class Sched>
; __device__ __forceinline__ void gemm_phase(LAS unsigned char* lds, const Gemm g, const Sched& S, const Epi& E) {
;     ...
;     const char* cA = (const char*)g.A + (size_t)cur.pm * tstepA; const char* cB = (const char*)g.Bt + (size_t)cur.pn * tstepB;
;     PG8_STAGE(PG8_SB(0, 0), cB, voffB); PG8_STAGE(PG8_SA(0, 0), cA, voffA); PG8_STAGE(PG8_SB(0, 1), cB + hstepB, voffB); PG8_STAGE(PG8_SA(0, 1), cA + hstepA, voffA);
;     if (wr == 1) PG8_BAR;
;     PG8_WAIT_V(4); PG8_BAR;
;     PG8_STAGE(PG8_SB(1, 0), cB + kstep, voffB); PG8_STAGE(PG8_SA(1, 0), cA + kstep, voffA); PG8_STAGE(PG8_SB(1, 1), cB + hstepB + kstep, voffB);
;     PG8_WAIT_V(6); PG8_BAR;
;     for (;;) {
;         const bool has_next = S.next(ui + 1, nxt);
;         const char* nA = has_next ? (const char*)g.A + (size_t)nxt.pm * tstepA : cA; const char* nB = has_next ? (const char*)g.Bt + (size_t)nxt.pn * tstepB : cB;
;         for (int t = 0; t < nt; t += 2) {
;             const bool last = (t == nt - 2);
;             const char* a1 = cA + (size_t)(t + 1) * kstep;
;             const char* a2 = last ? nA : cA + (size_t)(t + 2) * kstep; const char* b2 = last ? nB : cB + (size_t)(t + 2) * kstep;
;             const char* a3 = a2 + kstep; const char* b3 = b2 + kstep;
;             PG8_LDB(B0, 0, 0); PG8_SCHED; PG8_LDA(At, 0, 0); PG8_STAGE(PG8_SA(1, 1), a1 + hstepA, voffA);
;             PG8_WAIT_L(8); PG8_BAR; PG8_WAIT_L(0); PG8_MMA(0, 0, At, B0); PG8_BAR; PG8_SCHED;
;             PG8_LDB(B1, 0, 1); PG8_STAGE(PG8_SB(0, 0), b2, voffB);
;             PG8_BAR; PG8_WAIT_L(0); PG8_MMA(0, 1, At, B1); PG8_BAR;
;             PG8_LDA(At, 0, 1); PG8_STAGE(PG8_SA(0, 0), a2, voffA);
;             PG8_BAR; PG8_WAIT_L(0); PG8_MMA(1, 0, At, B0); PG8_BAR; PG8_SCHED;
;             PG8_STAGE(PG8_SB(0, 1), b2 + hstepB, voffB);
;             PG8_WAIT_V(6); PG8_BAR; PG8_MMA(1, 1, At, B1); PG8_BAR;
.LBB0_609:
	s_ashr_i32 s3, s2, 31
	s_lshl_b64 s[2:3], s[2:3], 22
	s_add_u32 s2, s6, s2
	s_addc_u32 s3, s7, s3
	s_add_i32 s31, 0, 0x18000
	s_add_i32 s24, s31, s30
	v_and_b32_e32 v18, 15, v1
	v_and_b32_e32 v19, 48, v1
	v_lshlrev_b32_e32 v1, 2, v1
	v_lshl_add_u64 v[26:27], v[12:13], 0, s[90:91]
	s_mov_b32 m0, s24
	s_add_i32 s25, s24, 0x2000
	v_lshlrev_b32_e32 v18, 6, v18
	v_and_b32_e32 v1, 32, v1
	s_lshl_b32 s20, s20, 12
	s_waitcnt vmcnt(4)
	s_barrier
	global_load_lds_dwordx4 v[26:27], off
	v_lshl_add_u64 v[28:29], v[16:17], 0, s[90:91]
	s_mov_b32 m0, s25
	s_add_i32 s22, s16, 0x8000
	v_or_b32_e32 v20, v18, v19
	v_bitop3_b32 v18, v18, v1, v19 bitop3:0x36
	s_and_b32 s20, s20, 0x3000
	global_load_lds_dwordx4 v[28:29], off
	v_lshl_add_u64 v[22:23], v[8:9], 0, s[90:91]
	s_mov_b32 m0, s22
	s_add_i32 s23, s16, 0xa000
	s_add_i32 s34, 0, 0x1c000
	s_lshl_b32 s21, s21, 13
	v_or_b32_e32 v30, s20, v18
	global_load_lds_dwordx4 v[22:23], off
	v_lshl_add_u64 v[24:25], v[14:15], 0, s[90:91]
	s_mov_b32 m0, s23
	s_add_i32 s20, s34, s30
	v_bitop3_b32 v1, v20, s21, v1 bitop3:0xde
	global_load_lds_dwordx4 v[24:25], off
	v_lshl_add_u64 v[18:19], v[6:7], 0, s[90:91]
	s_mov_b32 m0, s20
	s_add_i32 s21, s20, 0x2000
	global_load_lds_dwordx4 v[18:19], off
	v_lshl_add_u64 v[20:21], v[10:11], 0, s[90:91]
	s_mov_b32 m0, s21
	s_add_i32 s35, 0, 0x10000
	global_load_lds_dwordx4 v[20:21], off
	v_add_u32_e32 v198, s35, v30
	s_add_i32 s37, 0, 0x14000
	s_waitcnt vmcnt(6)
	s_barrier
	v_add_u32_e32 v199, s37, v30
	v_add_u32_e32 v230, s31, v30
	v_add_u32_e32 v238, s34, v30
	ds_read_b128 v[30:33], v198
	ds_read_b128 v[34:37], v198 offset:1024
	ds_read_b128 v[38:41], v198 offset:2048
	ds_read_b128 v[42:45], v198 offset:3072
	v_add_u32_e32 v1, 0, v1
	s_add_i32 s36, s16, 0xc000
	v_lshl_add_u64 v[78:79], v[2:3], 0, s[90:91]
	s_mov_b32 m0, s36
	s_add_i32 s31, s16, 0xe000
	ds_read_b128 v[46:49], v1
	ds_read_b128 v[50:53], v1 offset:1024
	ds_read_b128 v[54:57], v1 offset:2048
	ds_read_b128 v[58:61], v1 offset:3072
	ds_read_b128 v[62:65], v1 offset:4096
	ds_read_b128 v[66:69], v1 offset:5120
	ds_read_b128 v[70:73], v1 offset:6144
	ds_read_b128 v[74:77], v1 offset:7168
	global_load_lds_dwordx4 v[78:79], off
	v_lshl_add_u64 v[78:79], v[4:5], 0, s[90:91]
	s_mov_b32 m0, s31
	s_nop 0
	global_load_lds_dwordx4 v[78:79], off
	s_waitcnt lgkmcnt(8)
	s_barrier
	s_waitcnt lgkmcnt(0)
	s_setprio 1
	s_waitcnt lgkmcnt(0)
	v_mfma_f32_16x16x32_bf16 v[78:81], v[30:33], v[46:49], 0
	v_mfma_f32_16x16x32_bf16 v[82:85], v[38:41], v[46:49], 0
	v_mfma_f32_16x16x32_bf16 v[86:89], v[30:33], v[54:57], 0
	v_mfma_f32_16x16x32_bf16 v[90:93], v[38:41], v[54:57], 0
	v_mfma_f32_16x16x32_bf16 v[94:97], v[30:33], v[62:65], 0
	v_mfma_f32_16x16x32_bf16 v[98:101], v[38:41], v[62:65], 0
	v_mfma_f32_16x16x32_bf16 v[102:105], v[30:33], v[70:73], 0
	v_mfma_f32_16x16x32_bf16 v[106:109], v[38:41], v[70:73], 0
	v_mfma_f32_16x16x32_bf16 v[78:81], v[34:37], v[50:53], v[78:81]
	v_mfma_f32_16x16x32_bf16 v[82:85], v[42:45], v[50:53], v[82:85]
	v_mfma_f32_16x16x32_bf16 v[86:89], v[34:37], v[58:61], v[86:89]
	v_mfma_f32_16x16x32_bf16 v[90:93], v[42:45], v[58:61], v[90:93]
	v_mfma_f32_16x16x32_bf16 v[94:97], v[34:37], v[66:69], v[94:97]
	v_mfma_f32_16x16x32_bf16 v[98:101], v[42:45], v[66:69], v[98:101]
	v_mfma_f32_16x16x32_bf16 v[102:105], v[34:37], v[74:77], v[102:105]
	v_mfma_f32_16x16x32_bf16 v[106:109], v[42:45], v[74:77], v[106:109]
	s_setprio 0
	s_barrier
	s_mov_b64 s[38:39], 0x100
	s_add_i32 s34, s35, s30
	v_lshl_add_u64 v[126:127], v[12:13], 0, s[38:39]
	s_mov_b32 m0, s34
	s_add_i32 s35, s34, 0x2000
	ds_read_b128 v[110:113], v199
	ds_read_b128 v[114:117], v199 offset:1024
	ds_read_b128 v[118:121], v199 offset:2048
	ds_read_b128 v[122:125], v199 offset:3072
	global_load_lds_dwordx4 v[126:127], off
	v_lshl_add_u64 v[126:127], v[16:17], 0, s[38:39]
	s_mov_b32 m0, s35
	s_nop 0
	global_load_lds_dwordx4 v[126:127], off
	s_barrier
	s_waitcnt lgkmcnt(0)
	s_setprio 1
	s_waitcnt lgkmcnt(0)
	v_mfma_f32_16x16x32_bf16 v[126:129], v[110:113], v[46:49], 0
	v_mfma_f32_16x16x32_bf16 v[46:49], v[118:121], v[46:49], 0
	v_mfma_f32_16x16x32_bf16 v[126:129], v[114:117], v[50:53], v[126:129]
	v_mfma_f32_16x16x32_bf16 v[46:49], v[122:125], v[50:53], v[46:49]
	v_mfma_f32_16x16x32_bf16 v[50:53], v[110:113], v[54:57], 0
	v_mfma_f32_16x16x32_bf16 v[54:57], v[118:121], v[54:57], 0
	v_mfma_f32_16x16x32_bf16 v[50:53], v[114:117], v[58:61], v[50:53]
	v_mfma_f32_16x16x32_bf16 v[54:57], v[122:125], v[58:61], v[54:57]
	v_mfma_f32_16x16x32_bf16 v[58:61], v[110:113], v[62:65], 0
	v_mfma_f32_16x16x32_bf16 v[62:65], v[118:121], v[62:65], 0
	v_mfma_f32_16x16x32_bf16 v[58:61], v[114:117], v[66:69], v[58:61]
	v_mfma_f32_16x16x32_bf16 v[62:65], v[122:125], v[66:69], v[62:65]
	v_mfma_f32_16x16x32_bf16 v[66:69], v[110:113], v[70:73], 0
	v_mfma_f32_16x16x32_bf16 v[70:73], v[118:121], v[70:73], 0
	v_mfma_f32_16x16x32_bf16 v[66:69], v[114:117], v[74:77], v[66:69]
	v_mfma_f32_16x16x32_bf16 v[70:73], v[122:125], v[74:77], v[70:73]
	s_setprio 0
	s_mov_b32 m0, s16
	v_lshl_add_u64 v[158:159], v[8:9], 0, s[38:39]
	s_barrier
	ds_read_b128 v[74:77], v1 offset:16384
	ds_read_b128 v[130:133], v1 offset:17408
	ds_read_b128 v[134:137], v1 offset:18432
	ds_read_b128 v[138:141], v1 offset:19456
	ds_read_b128 v[142:145], v1 offset:20480
	ds_read_b128 v[146:149], v1 offset:21504
	ds_read_b128 v[150:153], v1 offset:22528
	ds_read_b128 v[154:157], v1 offset:23552
	global_load_lds_dwordx4 v[158:159], off
	v_lshl_add_u64 v[158:159], v[14:15], 0, s[38:39]
	s_mov_b32 m0, s19
	s_nop 0
	global_load_lds_dwordx4 v[158:159], off
	s_barrier
; #define PG8_STAGE(bufoff, gbase, voff) do { _Pragma("unroll") for (int _i = 0; _i < 2; ++_i) \
;         __builtin_amdgcn_global_load_lds((const unsigned*)((const char*)(gbase) + (voff)[_i]), (LAS unsigned*)(lds + (bufoff) + ldsw + _i * 8192), 16, 0, 0); } while (0)
; #define PG8_LDA(dst, b, h) do { _Pragma("unroll") for (int m = 0; m < 4; ++m) _Pragma("unroll") for (int k = 0; k < 2; ++k) dst[m][k] = *(const LAS bf16x8*)(lds + PG8_SA(b, h) + aoff + m * 2048 + k * 1024); } while (0)
; #define PG8_LDB(dst, b, h) do { _Pragma("unroll") for (int n = 0; n < 2; ++n) _Pragma("unroll") for (int k = 0; k < 2; ++k) dst[n][k] = *(const LAS bf16x8*)(lds + PG8_SB(b, h) + boff + n * 2048 + k * 1024); } while (0)
; #define PG8_WAIT_V(n) asm volatile("s_waitcnt vmcnt(" #n ")" ::: "memory")
; #define PG8_WAIT_L(n) asm volatile("s_waitcnt lgkmcnt(" #n ")" ::: "memory")
; #define PG8_BAR __builtin_amdgcn_s_barrier()
; #define PG8_SCHED __builtin_amdgcn_sched_barrier(0)
; template <class Epi, class Sched>
; __device__ __forceinline__ void gemm_phase(LAS unsigned char* lds, const Gemm g, const Sched& S, const Epi& E) {
;     ...
;             PG8_LDB(B0, 0, 0); PG8_SCHED; PG8_LDA(At, 0, 0); PG8_STAGE(PG8_SA(1, 1), a1 + hstepA, voffA);
;             PG8_WAIT_L(8); PG8_BAR; PG8_WAIT_L(0); PG8_MMA(0, 0, At, B0); PG8_BAR; PG8_SCHED;
;             PG8_LDB(B1, 0, 1); PG8_STAGE(PG8_SB(0, 0), b2, voffB);
;             PG8_BAR; PG8_WAIT_L(0); PG8_MMA(0, 1, At, B1); PG8_BAR;
;             PG8_LDA(At, 0, 1); PG8_STAGE(PG8_SA(0, 0), a2, voffA);
;             PG8_BAR; PG8_WAIT_L(0); PG8_MMA(1, 0, At, B0); PG8_BAR; PG8_SCHED;
;             PG8_STAGE(PG8_SB(0, 1), b2 + hstepB, voffB);
;             PG8_WAIT_V(6); PG8_BAR; PG8_MMA(1, 1, At, B1); PG8_BAR;
;             PG8_LDB(B0, 1, 0); PG8_SCHED; PG8_LDA(At, 1, 0); PG8_STAGE(PG8_SA(0, 1), a2 + hstepA, voffA);
;             PG8_WAIT_L(8); PG8_BAR; PG8_WAIT_L(0); PG8_MMA(0, 0, At, B0); PG8_BAR; PG8_SCHED;
;             PG8_LDB(B1, 1, 1); PG8_STAGE(PG8_SB(1, 0), b3, voffB);
;             PG8_BAR; PG8_WAIT_L(0); PG8_MMA(0, 1, At, B1); PG8_BAR;
;             PG8_LDA(At, 1, 1); PG8_STAGE(PG8_SA(1, 0), a3, voffA);
;             PG8_BAR; PG8_WAIT_L(0); PG8_MMA(1, 0, At, B0); PG8_BAR; PG8_SCHED;
;             PG8_STAGE(PG8_SB(1, 1), b3 + hstepB, voffB);
;             PG8_WAIT_V(6); PG8_BAR; PG8_MMA(1, 1, At, B1); PG8_BAR;
	s_waitcnt lgkmcnt(0)
	s_setprio 1
	s_waitcnt lgkmcnt(0)
	v_mfma_f32_16x16x32_bf16 v[158:161], v[30:33], v[74:77], 0
	v_mfma_f32_16x16x32_bf16 v[166:169], v[30:33], v[134:137], 0
	v_mfma_f32_16x16x32_bf16 v[174:177], v[30:33], v[142:145], 0
	v_mfma_f32_16x16x32_bf16 v[30:33], v[30:33], v[150:153], 0
	v_mfma_f32_16x16x32_bf16 v[158:161], v[34:37], v[130:133], v[158:161]
	v_mfma_f32_16x16x32_bf16 v[162:165], v[38:41], v[74:77], 0
	v_mfma_f32_16x16x32_bf16 v[166:169], v[34:37], v[138:141], v[166:169]
	v_mfma_f32_16x16x32_bf16 v[170:173], v[38:41], v[134:137], 0
	v_mfma_f32_16x16x32_bf16 v[174:177], v[34:37], v[146:149], v[174:177]
	v_mfma_f32_16x16x32_bf16 v[178:181], v[38:41], v[142:145], 0
	v_mfma_f32_16x16x32_bf16 v[30:33], v[34:37], v[154:157], v[30:33]
	v_mfma_f32_16x16x32_bf16 v[34:37], v[38:41], v[150:153], 0
	v_mfma_f32_16x16x32_bf16 v[162:165], v[42:45], v[130:133], v[162:165]
	v_mfma_f32_16x16x32_bf16 v[170:173], v[42:45], v[138:141], v[170:173]
	v_mfma_f32_16x16x32_bf16 v[178:181], v[42:45], v[146:149], v[178:181]
	v_mfma_f32_16x16x32_bf16 v[34:37], v[42:45], v[154:157], v[34:37]
	s_setprio 0
	s_barrier
	s_add_i32 s30, s37, s30
	v_lshl_add_u64 v[38:39], v[6:7], 0, s[38:39]
	s_mov_b32 m0, s30
	s_add_i32 s37, s30, 0x2000
	global_load_lds_dwordx4 v[38:39], off
	v_lshl_add_u64 v[38:39], v[10:11], 0, s[38:39]
	s_mov_b32 m0, s37
	s_nop 0
	global_load_lds_dwordx4 v[38:39], off
	s_waitcnt vmcnt(6)
	s_barrier
	s_setprio 1
	v_mfma_f32_16x16x32_bf16 v[38:41], v[110:113], v[74:77], 0
	v_mfma_f32_16x16x32_bf16 v[42:45], v[118:121], v[74:77], 0
	v_mfma_f32_16x16x32_bf16 v[38:41], v[114:117], v[130:133], v[38:41]
	v_mfma_f32_16x16x32_bf16 v[42:45], v[122:125], v[130:133], v[42:45]
	v_mfma_f32_16x16x32_bf16 v[74:77], v[110:113], v[134:137], 0
	v_mfma_f32_16x16x32_bf16 v[130:133], v[118:121], v[134:137], 0
	v_mfma_f32_16x16x32_bf16 v[134:137], v[110:113], v[142:145], 0
	v_mfma_f32_16x16x32_bf16 v[110:113], v[110:113], v[150:153], 0
	v_mfma_f32_16x16x32_bf16 v[74:77], v[114:117], v[138:141], v[74:77]
	v_mfma_f32_16x16x32_bf16 v[130:133], v[122:125], v[138:141], v[130:133]
	v_mfma_f32_16x16x32_bf16 v[134:137], v[114:117], v[146:149], v[134:137]
	v_mfma_f32_16x16x32_bf16 v[138:141], v[118:121], v[142:145], 0
	v_mfma_f32_16x16x32_bf16 v[110:113], v[114:117], v[154:157], v[110:113]
	v_mfma_f32_16x16x32_bf16 v[114:117], v[118:121], v[150:153], 0
	v_mfma_f32_16x16x32_bf16 v[138:141], v[122:125], v[146:149], v[138:141]
	v_mfma_f32_16x16x32_bf16 v[114:117], v[122:125], v[154:157], v[114:117]
	s_setprio 0
	s_barrier
	ds_read_b128 v[118:121], v230
	ds_read_b128 v[122:125], v230 offset:1024
	ds_read_b128 v[142:145], v230 offset:2048
	ds_read_b128 v[146:149], v230 offset:3072
	s_mov_b32 m0, s17
	v_lshl_add_u64 v[186:187], v[2:3], 0, s[38:39]
	ds_read_b128 v[150:153], v1 offset:32768
	ds_read_b128 v[154:157], v1 offset:33792
	ds_read_b128 v[182:185], v1 offset:34816
	ds_read_b128 v[190:193], v1 offset:35840
	ds_read_b128 v[194:197], v1 offset:36864
	ds_read_b128 v[200:203], v1 offset:37888
	ds_read_b128 v[204:207], v1 offset:38912
	ds_read_b128 v[208:211], v1 offset:39936
	global_load_lds_dwordx4 v[186:187], off
	v_lshl_add_u64 v[186:187], v[4:5], 0, s[38:39]
	s_mov_b32 m0, s18
	s_nop 0
	global_load_lds_dwordx4 v[186:187], off
	s_waitcnt lgkmcnt(8)
	s_barrier
	s_waitcnt lgkmcnt(0)
	s_setprio 1
	s_waitcnt lgkmcnt(0)
	v_mfma_f32_16x16x32_bf16 v[78:81], v[118:121], v[150:153], v[78:81]
	v_mfma_f32_16x16x32_bf16 v[82:85], v[142:145], v[150:153], v[82:85]
	v_mfma_f32_16x16x32_bf16 v[86:89], v[118:121], v[182:185], v[86:89]
	v_mfma_f32_16x16x32_bf16 v[90:93], v[142:145], v[182:185], v[90:93]
	v_mfma_f32_16x16x32_bf16 v[94:97], v[118:121], v[194:197], v[94:97]
	v_mfma_f32_16x16x32_bf16 v[98:101], v[142:145], v[194:197], v[98:101]
	v_mfma_f32_16x16x32_bf16 v[102:105], v[118:121], v[204:207], v[102:105]
	v_mfma_f32_16x16x32_bf16 v[106:109], v[142:145], v[204:207], v[106:109]
	v_mfma_f32_16x16x32_bf16 v[78:81], v[122:125], v[154:157], v[78:81]
	v_mfma_f32_16x16x32_bf16 v[82:85], v[146:149], v[154:157], v[82:85]
	v_mfma_f32_16x16x32_bf16 v[86:89], v[122:125], v[190:193], v[86:89]
	v_mfma_f32_16x16x32_bf16 v[90:93], v[146:149], v[190:193], v[90:93]
	v_mfma_f32_16x16x32_bf16 v[94:97], v[122:125], v[200:203], v[94:97]
	v_mfma_f32_16x16x32_bf16 v[98:101], v[146:149], v[200:203], v[98:101]
	v_mfma_f32_16x16x32_bf16 v[102:105], v[122:125], v[208:211], v[102:105]
	v_mfma_f32_16x16x32_bf16 v[106:109], v[146:149], v[208:211], v[106:109]
	s_setprio 0
	s_barrier
	s_mov_b64 s[38:39], 0x180
	s_mov_b32 m0, s24
	v_lshl_add_u64 v[186:187], v[12:13], 0, s[38:39]
	ds_read_b128 v[212:215], v238
	ds_read_b128 v[216:219], v238 offset:1024
	ds_read_b128 v[222:225], v238 offset:2048
	ds_read_b128 v[226:229], v238 offset:3072
	global_load_lds_dwordx4 v[186:187], off
	v_lshl_add_u64 v[186:187], v[16:17], 0, s[38:39]
	s_mov_b32 m0, s25
	s_nop 0
	global_load_lds_dwordx4 v[186:187], off
	s_barrier
	s_waitcnt lgkmcnt(0)
	s_setprio 1
	s_waitcnt lgkmcnt(0)
	v_mfma_f32_16x16x32_bf16 v[126:129], v[212:215], v[150:153], v[126:129]
	v_mfma_f32_16x16x32_bf16 v[46:49], v[222:225], v[150:153], v[46:49]
	v_mfma_f32_16x16x32_bf16 v[50:53], v[212:215], v[182:185], v[50:53]
	v_mfma_f32_16x16x32_bf16 v[54:57], v[222:225], v[182:185], v[54:57]
	v_mfma_f32_16x16x32_bf16 v[58:61], v[212:215], v[194:197], v[58:61]
	v_mfma_f32_16x16x32_bf16 v[62:65], v[222:225], v[194:197], v[62:65]
	v_mfma_f32_16x16x32_bf16 v[66:69], v[212:215], v[204:207], v[66:69]
	v_mfma_f32_16x16x32_bf16 v[70:73], v[222:225], v[204:207], v[70:73]
	v_mfma_f32_16x16x32_bf16 v[126:129], v[216:219], v[154:157], v[126:129]
	v_mfma_f32_16x16x32_bf16 v[46:49], v[226:229], v[154:157], v[46:49]
	v_mfma_f32_16x16x32_bf16 v[50:53], v[216:219], v[190:193], v[50:53]
	v_mfma_f32_16x16x32_bf16 v[54:57], v[226:229], v[190:193], v[54:57]
	v_mfma_f32_16x16x32_bf16 v[58:61], v[216:219], v[200:203], v[58:61]
	v_mfma_f32_16x16x32_bf16 v[62:65], v[226:229], v[200:203], v[62:65]
	v_mfma_f32_16x16x32_bf16 v[66:69], v[216:219], v[208:211], v[66:69]
	v_mfma_f32_16x16x32_bf16 v[70:73], v[226:229], v[208:211], v[70:73]
	s_setprio 0
	s_mov_b32 m0, s22
	v_lshl_add_u64 v[186:187], v[8:9], 0, s[38:39]
	s_barrier
; #define PG8_STAGE(bufoff, gbase, voff) do { _Pragma("unroll") for (int _i = 0; _i < 2; ++_i) \
;         __builtin_amdgcn_global_load_lds((const unsigned*)((const char*)(gbase) + (voff)[_i]), (LAS unsigned*)(lds + (bufoff) + ldsw + _i * 8192), 16, 0, 0); } while (0)
; #define PG8_LDA(dst, b, h) do { _Pragma("unroll") for (int m = 0; m < 4; ++m) _Pragma("unroll") for (int k = 0; k < 2; ++k) dst[m][k] = *(const LAS bf16x8*)(lds + PG8_SA(b, h) + aoff + m * 2048 + k * 1024); } while (0)
; #define PG8_LDB(dst, b, h) do { _Pragma("unroll") for (int n = 0; n < 2; ++n) _Pragma("unroll") for (int k = 0; k < 2; ++k) dst[n][k] = *(const LAS bf16x8*)(lds + PG8_SB(b, h) + boff + n * 2048 + k * 1024); } while (0)
; #define PG8_WAIT_V(n) asm volatile("s_waitcnt vmcnt(" #n ")" ::: "memory")
; #define PG8_WAIT_L(n) asm volatile("s_waitcnt lgkmcnt(" #n ")" ::: "memory")
; #define PG8_BAR __builtin_amdgcn_s_barrier()
; #define PG8_SCHED __builtin_amdgcn_sched_barrier(0)
; template <class Epi, class Sched>
; __device__ __forceinline__ void gemm_phase(LAS unsigned char* lds, const Gemm g, const Sched& S, const Epi& E) {
;     ...
;             PG8_LDB(B0, 0, 0); PG8_SCHED; PG8_LDA(At, 0, 0); PG8_STAGE(PG8_SA(1, 1), a1 + hstepA, voffA);
;             PG8_WAIT_L(8); PG8_BAR; PG8_WAIT_L(0); PG8_MMA(0, 0, At, B0); PG8_BAR; PG8_SCHED;
;             PG8_LDB(B1, 0, 1); PG8_STAGE(PG8_SB(0, 0), b2, voffB);
;             PG8_BAR; PG8_WAIT_L(0); PG8_MMA(0, 1, At, B1); PG8_BAR;
;             PG8_LDA(At, 0, 1); PG8_STAGE(PG8_SA(0, 0), a2, voffA);
;             PG8_BAR; PG8_WAIT_L(0); PG8_MMA(1, 0, At, B0); PG8_BAR; PG8_SCHED;
;             PG8_STAGE(PG8_SB(0, 1), b2 + hstepB, voffB);
;             PG8_WAIT_V(6); PG8_BAR; PG8_MMA(1, 1, At, B1); PG8_BAR;
;             PG8_LDB(B0, 1, 0); PG8_SCHED; PG8_LDA(At, 1, 0); PG8_STAGE(PG8_SA(0, 1), a2 + hstepA, voffA);
;             PG8_WAIT_L(8); PG8_BAR; PG8_WAIT_L(0); PG8_MMA(0, 0, At, B0); PG8_BAR; PG8_SCHED;
;             PG8_LDB(B1, 1, 1); PG8_STAGE(PG8_SB(1, 0), b3, voffB);
;             PG8_BAR; PG8_WAIT_L(0); PG8_MMA(0, 1, At, B1); PG8_BAR;
;             PG8_LDA(At, 1, 1); PG8_STAGE(PG8_SA(1, 0), a3, voffA);
;             PG8_BAR; PG8_WAIT_L(0); PG8_MMA(1, 0, At, B0); PG8_BAR; PG8_SCHED;
;             PG8_STAGE(PG8_SB(1, 1), b3 + hstepB, voffB);
;             PG8_WAIT_V(6); PG8_BAR; PG8_MMA(1, 1, At, B1); PG8_BAR;
	ds_read_b128 v[150:153], v1 offset:49152
	ds_read_b128 v[154:157], v1 offset:50176
	ds_read_b128 v[182:185], v1 offset:51200
	ds_read_b128 v[190:193], v1 offset:52224
	ds_read_b128 v[194:197], v1 offset:53248
	ds_read_b128 v[200:203], v1 offset:54272
	ds_read_b128 v[204:207], v1 offset:55296
	ds_read_b128 v[208:211], v1 offset:56320
	global_load_lds_dwordx4 v[186:187], off
	v_lshl_add_u64 v[186:187], v[14:15], 0, s[38:39]
	s_mov_b32 m0, s23
	s_nop 0
	global_load_lds_dwordx4 v[186:187], off
	s_barrier
	s_waitcnt lgkmcnt(0)
	s_setprio 1
	s_waitcnt lgkmcnt(0)
	v_mfma_f32_16x16x32_bf16 v[158:161], v[118:121], v[150:153], v[158:161]
	v_mfma_f32_16x16x32_bf16 v[162:165], v[142:145], v[150:153], v[162:165]
	v_mfma_f32_16x16x32_bf16 v[166:169], v[118:121], v[182:185], v[166:169]
	v_mfma_f32_16x16x32_bf16 v[170:173], v[142:145], v[182:185], v[170:173]
	v_mfma_f32_16x16x32_bf16 v[174:177], v[118:121], v[194:197], v[174:177]
	v_mfma_f32_16x16x32_bf16 v[178:181], v[142:145], v[194:197], v[178:181]
	v_mfma_f32_16x16x32_bf16 v[30:33], v[118:121], v[204:207], v[30:33]
	v_mfma_f32_16x16x32_bf16 v[34:37], v[142:145], v[204:207], v[34:37]
	v_mfma_f32_16x16x32_bf16 v[158:161], v[122:125], v[154:157], v[158:161]
	v_mfma_f32_16x16x32_bf16 v[162:165], v[146:149], v[154:157], v[162:165]
	v_mfma_f32_16x16x32_bf16 v[166:169], v[122:125], v[190:193], v[166:169]
	v_mfma_f32_16x16x32_bf16 v[170:173], v[146:149], v[190:193], v[170:173]
	v_mfma_f32_16x16x32_bf16 v[174:177], v[122:125], v[200:203], v[174:177]
	v_mfma_f32_16x16x32_bf16 v[178:181], v[146:149], v[200:203], v[178:181]
	v_mfma_f32_16x16x32_bf16 v[30:33], v[122:125], v[208:211], v[30:33]
	v_mfma_f32_16x16x32_bf16 v[34:37], v[146:149], v[208:211], v[34:37]
	s_setprio 0
	s_barrier
	s_mov_b32 m0, s20
	v_lshl_add_u64 v[118:119], v[6:7], 0, s[38:39]
	global_load_lds_dwordx4 v[118:119], off
	v_lshl_add_u64 v[118:119], v[10:11], 0, s[38:39]
	s_mov_b32 m0, s21
	s_nop 0
	global_load_lds_dwordx4 v[118:119], off
	s_waitcnt vmcnt(6)
	s_barrier
	s_setprio 1
	v_mfma_f32_16x16x32_bf16 v[38:41], v[212:215], v[150:153], v[38:41]
	v_mfma_f32_16x16x32_bf16 v[42:45], v[222:225], v[150:153], v[42:45]
	v_mfma_f32_16x16x32_bf16 v[74:77], v[212:215], v[182:185], v[74:77]
	v_mfma_f32_16x16x32_bf16 v[118:121], v[222:225], v[182:185], v[130:133]
	v_mfma_f32_16x16x32_bf16 v[122:125], v[212:215], v[194:197], v[134:137]
	v_mfma_f32_16x16x32_bf16 v[130:133], v[222:225], v[194:197], v[138:141]
	v_mfma_f32_16x16x32_bf16 v[110:113], v[212:215], v[204:207], v[110:113]
	v_mfma_f32_16x16x32_bf16 v[114:117], v[222:225], v[204:207], v[114:117]
	v_mfma_f32_16x16x32_bf16 v[38:41], v[216:219], v[154:157], v[38:41]
	v_mfma_f32_16x16x32_bf16 v[42:45], v[226:229], v[154:157], v[42:45]
	v_mfma_f32_16x16x32_bf16 v[74:77], v[216:219], v[190:193], v[74:77]
	v_mfma_f32_16x16x32_bf16 v[118:121], v[226:229], v[190:193], v[118:121]
	v_mfma_f32_16x16x32_bf16 v[122:125], v[216:219], v[200:203], v[122:125]
	v_mfma_f32_16x16x32_bf16 v[130:133], v[226:229], v[200:203], v[130:133]
	v_mfma_f32_16x16x32_bf16 v[110:113], v[216:219], v[208:211], v[110:113]
	v_mfma_f32_16x16x32_bf16 v[114:117], v[226:229], v[208:211], v[114:117]
	s_setprio 0
	s_barrier
	ds_read_b128 v[134:137], v198
	ds_read_b128 v[138:141], v198 offset:1024
	ds_read_b128 v[142:145], v198 offset:2048
	ds_read_b128 v[146:149], v198 offset:3072
	s_mov_b32 m0, s36
	v_lshl_add_u64 v[186:187], v[2:3], 0, s[38:39]
	ds_read_b128 v[150:153], v1
	ds_read_b128 v[154:157], v1 offset:1024
	ds_read_b128 v[182:185], v1 offset:2048
	ds_read_b128 v[190:193], v1 offset:3072
	ds_read_b128 v[194:197], v1 offset:4096
	ds_read_b128 v[200:203], v1 offset:5120
	ds_read_b128 v[204:207], v1 offset:6144
	ds_read_b128 v[208:211], v1 offset:7168
	global_load_lds_dwordx4 v[186:187], off
	v_lshl_add_u64 v[186:187], v[4:5], 0, s[38:39]
	s_mov_b32 m0, s31
	s_nop 0
	global_load_lds_dwordx4 v[186:187], off
	s_waitcnt lgkmcnt(8)
	s_barrier
	s_waitcnt lgkmcnt(0)
	s_setprio 1
	s_waitcnt lgkmcnt(0)
	v_mfma_f32_16x16x32_bf16 v[98:101], v[142:145], v[194:197], v[98:101]
	v_mfma_f32_16x16x32_bf16 v[212:215], v[146:149], v[200:203], v[98:101]
	v_mfma_f32_16x16x32_bf16 v[98:101], v[134:137], v[204:207], v[102:105]
	v_mfma_f32_16x16x32_bf16 v[78:81], v[134:137], v[150:153], v[78:81]
	v_mfma_f32_16x16x32_bf16 v[82:85], v[142:145], v[150:153], v[82:85]
	v_mfma_f32_16x16x32_bf16 v[86:89], v[134:137], v[182:185], v[86:89]
	v_mfma_f32_16x16x32_bf16 v[90:93], v[142:145], v[182:185], v[90:93]
	v_mfma_f32_16x16x32_bf16 v[94:97], v[134:137], v[194:197], v[94:97]
	v_mfma_f32_16x16x32_bf16 v[102:105], v[138:141], v[208:211], v[98:101]
	v_mfma_f32_16x16x32_bf16 v[98:101], v[142:145], v[204:207], v[106:109]
	v_mfma_f32_16x16x32_bf16 v[78:81], v[138:141], v[154:157], v[78:81]
	v_mfma_f32_16x16x32_bf16 v[82:85], v[146:149], v[154:157], v[82:85]
	v_mfma_f32_16x16x32_bf16 v[86:89], v[138:141], v[190:193], v[86:89]
	v_mfma_f32_16x16x32_bf16 v[90:93], v[146:149], v[190:193], v[90:93]
	v_mfma_f32_16x16x32_bf16 v[94:97], v[138:141], v[200:203], v[94:97]
	v_mfma_f32_16x16x32_bf16 v[106:109], v[146:149], v[208:211], v[98:101]
	s_setprio 0
	s_barrier
	s_mov_b32 m0, s34
	ds_read_b128 v[98:101], v199
	ds_read_b128 v[216:219], v199 offset:1024
	ds_read_b128 v[222:225], v199 offset:2048
	ds_read_b128 v[226:229], v199 offset:3072
	global_load_lds_dwordx4 v[12:13], off
	s_mov_b32 m0, s35
	s_nop 0
	global_load_lds_dwordx4 v[16:17], off
	s_barrier
; #define PG8_STAGE(bufoff, gbase, voff) do { _Pragma("unroll") for (int _i = 0; _i < 2; ++_i) \
;         __builtin_amdgcn_global_load_lds((const unsigned*)((const char*)(gbase) + (voff)[_i]), (LAS unsigned*)(lds + (bufoff) + ldsw + _i * 8192), 16, 0, 0); } while (0)
; #define PG8_LDA(dst, b, h) do { _Pragma("unroll") for (int m = 0; m < 4; ++m) _Pragma("unroll") for (int k = 0; k < 2; ++k) dst[m][k] = *(const LAS bf16x8*)(lds + PG8_SA(b, h) + aoff + m * 2048 + k * 1024); } while (0)
; #define PG8_LDB(dst, b, h) do { _Pragma("unroll") for (int n = 0; n < 2; ++n) _Pragma("unroll") for (int k = 0; k < 2; ++k) dst[n][k] = *(const LAS bf16x8*)(lds + PG8_SB(b, h) + boff + n * 2048 + k * 1024); } while (0)
; #define PG8_WAIT_V(n) asm volatile("s_waitcnt vmcnt(" #n ")" ::: "memory")
; #define PG8_WAIT_L(n) asm volatile("s_waitcnt lgkmcnt(" #n ")" ::: "memory")
; #define PG8_BAR __builtin_amdgcn_s_barrier()
; #define PG8_SCHED __builtin_amdgcn_sched_barrier(0)
; template <class Epi, class Sched>
; __device__ __forceinline__ void gemm_phase(LAS unsigned char* lds, const Gemm g, const Sched& S, const Epi& E) {
;     ...
;             PG8_LDB(B0, 0, 0); PG8_SCHED; PG8_LDA(At, 0, 0); PG8_STAGE(PG8_SA(1, 1), a1 + hstepA, voffA);
;             PG8_WAIT_L(8); PG8_BAR; PG8_WAIT_L(0); PG8_MMA(0, 0, At, B0); PG8_BAR; PG8_SCHED;
;             PG8_LDB(B1, 0, 1); PG8_STAGE(PG8_SB(0, 0), b2, voffB);
;             PG8_BAR; PG8_WAIT_L(0); PG8_MMA(0, 1, At, B1); PG8_BAR;
;             PG8_LDA(At, 0, 1); PG8_STAGE(PG8_SA(0, 0), a2, voffA);
;             PG8_BAR; PG8_WAIT_L(0); PG8_MMA(1, 0, At, B0); PG8_BAR; PG8_SCHED;
;             PG8_STAGE(PG8_SB(0, 1), b2 + hstepB, voffB);
;             PG8_WAIT_V(6); PG8_BAR; PG8_MMA(1, 1, At, B1); PG8_BAR;
;             PG8_LDB(B0, 1, 0); PG8_SCHED; PG8_LDA(At, 1, 0); PG8_STAGE(PG8_SA(0, 1), a2 + hstepA, voffA);
;             PG8_WAIT_L(8); PG8_BAR; PG8_WAIT_L(0); PG8_MMA(0, 0, At, B0); PG8_BAR; PG8_SCHED;
;             PG8_LDB(B1, 1, 1); PG8_STAGE(PG8_SB(1, 0), b3, voffB);
;             PG8_BAR; PG8_WAIT_L(0); PG8_MMA(0, 1, At, B1); PG8_BAR;
;             PG8_LDA(At, 1, 1); PG8_STAGE(PG8_SA(1, 0), a3, voffA);
;             PG8_BAR; PG8_WAIT_L(0); PG8_MMA(1, 0, At, B0); PG8_BAR; PG8_SCHED;
;             PG8_STAGE(PG8_SB(1, 1), b3 + hstepB, voffB);
;             PG8_WAIT_V(6); PG8_BAR; PG8_MMA(1, 1, At, B1); PG8_BAR;
	s_waitcnt lgkmcnt(0)
	s_setprio 1
	s_waitcnt lgkmcnt(0)
	v_mfma_f32_16x16x32_bf16 v[62:65], v[222:225], v[194:197], v[62:65]
	v_mfma_f32_16x16x32_bf16 v[126:129], v[98:101], v[150:153], v[126:129]
	v_mfma_f32_16x16x32_bf16 v[46:49], v[222:225], v[150:153], v[46:49]
	v_mfma_f32_16x16x32_bf16 v[150:153], v[226:229], v[200:203], v[62:65]
	v_mfma_f32_16x16x32_bf16 v[62:65], v[98:101], v[204:207], v[66:69]
	v_mfma_f32_16x16x32_bf16 v[50:53], v[98:101], v[182:185], v[50:53]
	v_mfma_f32_16x16x32_bf16 v[54:57], v[222:225], v[182:185], v[54:57]
	v_mfma_f32_16x16x32_bf16 v[58:61], v[98:101], v[194:197], v[58:61]
	v_mfma_f32_16x16x32_bf16 v[66:69], v[216:219], v[208:211], v[62:65]
	v_mfma_f32_16x16x32_bf16 v[62:65], v[222:225], v[204:207], v[70:73]
	v_mfma_f32_16x16x32_bf16 v[126:129], v[216:219], v[154:157], v[126:129]
	v_mfma_f32_16x16x32_bf16 v[46:49], v[226:229], v[154:157], v[46:49]
	v_mfma_f32_16x16x32_bf16 v[50:53], v[216:219], v[190:193], v[50:53]
	v_mfma_f32_16x16x32_bf16 v[54:57], v[226:229], v[190:193], v[54:57]
	v_mfma_f32_16x16x32_bf16 v[58:61], v[216:219], v[200:203], v[58:61]
	v_mfma_f32_16x16x32_bf16 v[70:73], v[226:229], v[208:211], v[62:65]
	s_setprio 0
	s_mov_b32 m0, s16
	s_barrier
	ds_read_b128 v[62:65], v1 offset:16384
	ds_read_b128 v[154:157], v1 offset:17408
	ds_read_b128 v[182:185], v1 offset:18432
	ds_read_b128 v[190:193], v1 offset:19456
	ds_read_b128 v[194:197], v1 offset:20480
	ds_read_b128 v[200:203], v1 offset:21504
	ds_read_b128 v[204:207], v1 offset:22528
	ds_read_b128 v[208:211], v1 offset:23552
	global_load_lds_dwordx4 v[8:9], off
	s_mov_b32 m0, s19
	s_nop 0
	global_load_lds_dwordx4 v[14:15], off
	s_barrier
	s_waitcnt lgkmcnt(0)
	s_setprio 1
	s_waitcnt lgkmcnt(0)
	v_mfma_f32_16x16x32_bf16 v[30:33], v[134:137], v[204:207], v[30:33]
	v_mfma_f32_16x16x32_bf16 v[12:15], v[134:137], v[62:65], v[158:161]
	v_mfma_f32_16x16x32_bf16 v[158:161], v[142:145], v[62:65], v[162:165]
	v_mfma_f32_16x16x32_bf16 v[162:165], v[134:137], v[182:185], v[166:169]
	v_mfma_f32_16x16x32_bf16 v[166:169], v[142:145], v[182:185], v[170:173]
	v_mfma_f32_16x16x32_bf16 v[170:173], v[134:137], v[194:197], v[174:177]
	v_mfma_f32_16x16x32_bf16 v[174:177], v[142:145], v[194:197], v[178:181]
	v_mfma_f32_16x16x32_bf16 v[134:137], v[138:141], v[208:211], v[30:33]
	v_mfma_f32_16x16x32_bf16 v[30:33], v[142:145], v[204:207], v[34:37]
	v_mfma_f32_16x16x32_bf16 v[12:15], v[138:141], v[154:157], v[12:15]
	v_mfma_f32_16x16x32_bf16 v[158:161], v[146:149], v[154:157], v[158:161]
	v_mfma_f32_16x16x32_bf16 v[162:165], v[138:141], v[190:193], v[162:165]
	v_mfma_f32_16x16x32_bf16 v[166:169], v[146:149], v[190:193], v[166:169]
	v_mfma_f32_16x16x32_bf16 v[170:173], v[138:141], v[200:203], v[170:173]
	v_mfma_f32_16x16x32_bf16 v[174:177], v[146:149], v[200:203], v[174:177]
	v_mfma_f32_16x16x32_bf16 v[34:37], v[146:149], v[208:211], v[30:33]
	s_setprio 0
	s_barrier
	s_mov_b32 m0, s30
	s_nop 0
	global_load_lds_dwordx4 v[6:7], off
	s_mov_b32 m0, s37
	s_nop 0
	global_load_lds_dwordx4 v[10:11], off
	s_waitcnt vmcnt(6)
	s_barrier
	s_setprio 1
	v_mfma_f32_16x16x32_bf16 v[6:9], v[98:101], v[62:65], v[38:41]
	v_mfma_f32_16x16x32_bf16 v[138:141], v[216:219], v[154:157], v[6:9]
	v_mfma_f32_16x16x32_bf16 v[6:9], v[222:225], v[62:65], v[42:45]
	v_mfma_f32_16x16x32_bf16 v[42:45], v[226:229], v[154:157], v[6:9]
	v_mfma_f32_16x16x32_bf16 v[6:9], v[98:101], v[182:185], v[74:77]
	v_mfma_f32_16x16x32_bf16 v[142:145], v[216:219], v[190:193], v[6:9]
	v_mfma_f32_16x16x32_bf16 v[6:9], v[222:225], v[182:185], v[118:121]
	v_mfma_f32_16x16x32_bf16 v[146:149], v[226:229], v[190:193], v[6:9]
	v_mfma_f32_16x16x32_bf16 v[6:9], v[98:101], v[194:197], v[122:125]
	v_mfma_f32_16x16x32_bf16 v[154:157], v[216:219], v[200:203], v[6:9]
	v_mfma_f32_16x16x32_bf16 v[6:9], v[222:225], v[194:197], v[130:133]
	v_mfma_f32_16x16x32_bf16 v[130:133], v[226:229], v[200:203], v[6:9]
	v_mfma_f32_16x16x32_bf16 v[6:9], v[98:101], v[204:207], v[110:113]
	v_mfma_f32_16x16x32_bf16 v[178:181], v[216:219], v[208:211], v[6:9]
	v_mfma_f32_16x16x32_bf16 v[6:9], v[222:225], v[204:207], v[114:117]
	v_mfma_f32_16x16x32_bf16 v[182:185], v[226:229], v[208:211], v[6:9]
	s_setprio 0
	s_barrier
	s_nop 4
	ds_read_b128 v[6:9], v230
	ds_read_b128 v[190:193], v230 offset:1024
	ds_read_b128 v[194:197], v230 offset:2048
	ds_read_b128 v[200:203], v230 offset:3072
	s_mov_b32 m0, s17
	ds_read_b128 v[30:33], v1 offset:32768
	ds_read_b128 v[38:41], v1 offset:33792
	ds_read_b128 v[74:77], v1 offset:34816
	ds_read_b128 v[204:207], v1 offset:35840
	ds_read_b128 v[208:211], v1 offset:36864
	ds_read_b128 v[216:219], v1 offset:37888
	ds_read_b128 v[222:225], v1 offset:38912
	ds_read_b128 v[226:229], v1 offset:39936
	global_load_lds_dwordx4 v[2:3], off
	s_mov_b32 m0, s18
	s_nop 0
	global_load_lds_dwordx4 v[4:5], off
	s_waitcnt lgkmcnt(8)
	s_barrier
	s_waitcnt lgkmcnt(0)
	s_setprio 1
	s_waitcnt lgkmcnt(0)
	v_mfma_f32_16x16x32_bf16 v[2:5], v[6:9], v[30:33], v[78:81]
	v_mfma_f32_16x16x32_bf16 v[230:233], v[190:193], v[38:41], v[2:5]
	v_mfma_f32_16x16x32_bf16 v[2:5], v[194:197], v[30:33], v[82:85]
	v_mfma_f32_16x16x32_bf16 v[122:125], v[200:203], v[38:41], v[2:5]
	v_mfma_f32_16x16x32_bf16 v[2:5], v[6:9], v[74:77], v[86:89]
	v_mfma_f32_16x16x32_bf16 v[110:113], v[190:193], v[204:207], v[2:5]
	v_mfma_f32_16x16x32_bf16 v[2:5], v[194:197], v[74:77], v[90:93]
	v_mfma_f32_16x16x32_bf16 v[98:101], v[200:203], v[204:207], v[2:5]
	v_mfma_f32_16x16x32_bf16 v[2:5], v[6:9], v[208:211], v[94:97]
	v_mfma_f32_16x16x32_bf16 v[94:97], v[190:193], v[216:219], v[2:5]
	v_mfma_f32_16x16x32_bf16 v[2:5], v[194:197], v[208:211], v[212:215]
	v_mfma_f32_16x16x32_bf16 v[82:85], v[200:203], v[216:219], v[2:5]
	v_mfma_f32_16x16x32_bf16 v[2:5], v[6:9], v[222:225], v[102:105]
	v_mfma_f32_16x16x32_bf16 v[78:81], v[190:193], v[226:229], v[2:5]
	v_mfma_f32_16x16x32_bf16 v[2:5], v[194:197], v[222:225], v[106:109]
	v_mfma_f32_16x16x32_bf16 v[62:65], v[200:203], v[226:229], v[2:5]
	s_setprio 0
	s_barrier
; #define PG8_STAGE(bufoff, gbase, voff) do { _Pragma("unroll") for (int _i = 0; _i < 2; ++_i) \
;         __builtin_amdgcn_global_load_lds((const unsigned*)((const char*)(gbase) + (voff)[_i]), (LAS unsigned*)(lds + (bufoff) + ldsw + _i * 8192), 16, 0, 0); } while (0)
; #define PG8_LDA(dst, b, h) do { _Pragma("unroll") for (int m = 0; m < 4; ++m) _Pragma("unroll") for (int k = 0; k < 2; ++k) dst[m][k] = *(const LAS bf16x8*)(lds + PG8_SA(b, h) + aoff + m * 2048 + k * 1024); } while (0)
; #define PG8_LDB(dst, b, h) do { _Pragma("unroll") for (int n = 0; n < 2; ++n) _Pragma("unroll") for (int k = 0; k < 2; ++k) dst[n][k] = *(const LAS bf16x8*)(lds + PG8_SB(b, h) + boff + n * 2048 + k * 1024); } while (0)
; #define PG8_MMA(ai, bj, At, Bt) do { __builtin_amdgcn_s_setprio(1); _Pragma("unroll") for (int m = 0; m < 4; ++m) _Pragma("unroll") for (int n = 0; n < 2; ++n) _Pragma("unroll") for (int k = 0; k < 2; ++k) \
;         acc[ai][bj][m][n] = __builtin_amdgcn_mfma_f32_16x16x32_bf16(Bt[n][k], At[m][k], acc[ai][bj][m][n], 0, 0, 0); __builtin_amdgcn_s_setprio(0); } while (0)
; #define PG8_WAIT_V(n) asm volatile("s_waitcnt vmcnt(" #n ")" ::: "memory")
; #define PG8_WAIT_L(n) asm volatile("s_waitcnt lgkmcnt(" #n ")" ::: "memory")
; template <class Epi, class Sched>
; __device__ __forceinline__ void gemm_phase(LAS unsigned char* lds, const Gemm g, const Sched& S, const Epi& E) {
;     ...
;             PG8_BAR; PG8_WAIT_L(0); PG8_MMA(1, 0, At, B0); PG8_BAR; PG8_SCHED;
;             PG8_STAGE(PG8_SB(0, 1), b2 + hstepB, voffB);
;             PG8_WAIT_V(6); PG8_BAR; PG8_MMA(1, 1, At, B1); PG8_BAR;
;             PG8_LDB(B0, 1, 0); PG8_SCHED; PG8_LDA(At, 1, 0); PG8_STAGE(PG8_SA(0, 1), a2 + hstepA, voffA);
;             PG8_WAIT_L(8); PG8_BAR; PG8_WAIT_L(0); PG8_MMA(0, 0, At, B0); PG8_BAR; PG8_SCHED;
;             PG8_LDB(B1, 1, 1); PG8_STAGE(PG8_SB(1, 0), b3, voffB);
;             PG8_BAR; PG8_WAIT_L(0); PG8_MMA(0, 1, At, B1); PG8_BAR;
;             PG8_LDA(At, 1, 1); PG8_STAGE(PG8_SA(1, 0), a3, voffA);
;             PG8_BAR; PG8_WAIT_L(0); PG8_MMA(1, 0, At, B0); PG8_BAR; PG8_SCHED;
;             PG8_STAGE(PG8_SB(1, 1), b3 + hstepB, voffB);
;             PG8_WAIT_V(6); PG8_BAR; PG8_MMA(1, 1, At, B1); PG8_BAR;
;             if constexpr (Epi::HOOK) { if ((((t + 2) & 3) == 0) && !last) E.hook(acc, cur, (t + 2) >> 2, wr, wc, fr, fq); }
;         }
;         E(acc, cur, wr, wc, fr, fq);
	s_mov_b32 m0, s24
	s_nop 3
	ds_read_b128 v[2:5], v238
	ds_read_b128 v[212:215], v238 offset:1024
	ds_read_b128 v[234:237], v238 offset:2048
	ds_read_b128 v[238:241], v238 offset:3072
	global_load_lds_dwordx4 v[26:27], off
	s_mov_b32 m0, s25
	s_nop 0
	global_load_lds_dwordx4 v[28:29], off
	s_barrier
	s_waitcnt lgkmcnt(0)
	s_setprio 1
	s_waitcnt lgkmcnt(0)
	v_mfma_f32_16x16x32_bf16 v[26:29], v[2:5], v[30:33], v[126:129]
	v_mfma_f32_16x16x32_bf16 v[118:121], v[212:215], v[38:41], v[26:29]
	v_mfma_f32_16x16x32_bf16 v[26:29], v[234:237], v[30:33], v[46:49]
	v_mfma_f32_16x16x32_bf16 v[114:117], v[238:241], v[38:41], v[26:29]
	v_mfma_f32_16x16x32_bf16 v[26:29], v[2:5], v[74:77], v[50:53]
	v_mfma_f32_16x16x32_bf16 v[106:109], v[212:215], v[204:207], v[26:29]
	v_mfma_f32_16x16x32_bf16 v[26:29], v[234:237], v[74:77], v[54:57]
	v_mfma_f32_16x16x32_bf16 v[102:105], v[238:241], v[204:207], v[26:29]
	v_mfma_f32_16x16x32_bf16 v[26:29], v[2:5], v[208:211], v[58:61]
	v_mfma_f32_16x16x32_bf16 v[90:93], v[212:215], v[216:219], v[26:29]
	v_mfma_f32_16x16x32_bf16 v[26:29], v[234:237], v[208:211], v[150:153]
	v_mfma_f32_16x16x32_bf16 v[86:89], v[238:241], v[216:219], v[26:29]
	v_mfma_f32_16x16x32_bf16 v[26:29], v[2:5], v[222:225], v[66:69]
	v_mfma_f32_16x16x32_bf16 v[74:77], v[212:215], v[226:229], v[26:29]
	v_mfma_f32_16x16x32_bf16 v[26:29], v[234:237], v[222:225], v[70:73]
	v_mfma_f32_16x16x32_bf16 v[66:69], v[238:241], v[226:229], v[26:29]
	s_setprio 0
	s_mov_b32 m0, s22
	s_barrier
	s_nop 3
	ds_read_b128 v[26:29], v1 offset:49152
	ds_read_b128 v[50:53], v1 offset:50176
	ds_read_b128 v[126:129], v1 offset:51200
	ds_read_b128 v[150:153], v1 offset:52224
	ds_read_b128 v[204:207], v1 offset:53248
	ds_read_b128 v[208:211], v1 offset:54272
	ds_read_b128 v[216:219], v1 offset:55296
	ds_read_b128 v[222:225], v1 offset:56320
	global_load_lds_dwordx4 v[22:23], off
	s_mov_b32 m0, s23
	s_nop 0
	global_load_lds_dwordx4 v[24:25], off
	s_barrier
	s_waitcnt lgkmcnt(0)
	s_setprio 1
	s_waitcnt lgkmcnt(0)
	v_mfma_f32_16x16x32_bf16 v[10:13], v[6:9], v[26:29], v[12:15]
	v_mfma_f32_16x16x32_bf16 v[70:73], v[190:193], v[50:53], v[10:13]
	v_mfma_f32_16x16x32_bf16 v[10:13], v[194:197], v[26:29], v[158:161]
	v_mfma_f32_16x16x32_bf16 v[54:57], v[200:203], v[50:53], v[10:13]
	v_mfma_f32_16x16x32_bf16 v[10:13], v[6:9], v[126:129], v[162:165]
	v_mfma_f32_16x16x32_bf16 v[46:49], v[190:193], v[150:153], v[10:13]
	v_mfma_f32_16x16x32_bf16 v[10:13], v[194:197], v[126:129], v[166:169]
	v_mfma_f32_16x16x32_bf16 v[38:41], v[200:203], v[150:153], v[10:13]
	v_mfma_f32_16x16x32_bf16 v[10:13], v[6:9], v[204:207], v[170:173]
	v_mfma_f32_16x16x32_bf16 v[6:9], v[6:9], v[216:219], v[134:137]
	v_mfma_f32_16x16x32_bf16 v[30:33], v[190:193], v[208:211], v[10:13]
	v_mfma_f32_16x16x32_bf16 v[10:13], v[194:197], v[204:207], v[174:177]
	v_mfma_f32_16x16x32_bf16 v[14:17], v[190:193], v[222:225], v[6:9]
	v_mfma_f32_16x16x32_bf16 v[6:9], v[194:197], v[216:219], v[34:37]
	v_mfma_f32_16x16x32_bf16 v[22:25], v[200:203], v[208:211], v[10:13]
	v_mfma_f32_16x16x32_bf16 v[6:9], v[200:203], v[222:225], v[6:9]
	s_setprio 0
	s_barrier
	s_mov_b32 m0, s20
	s_nop 0
	global_load_lds_dwordx4 v[18:19], off
	s_mov_b32 m0, s21
	s_nop 0
	global_load_lds_dwordx4 v[20:21], off
	s_waitcnt vmcnt(6)
	s_barrier
	s_setprio 1
	v_mfma_f32_16x16x32_bf16 v[10:13], v[2:5], v[26:29], v[138:141]
	v_mfma_f32_16x16x32_bf16 v[58:61], v[212:215], v[50:53], v[10:13]
	v_mfma_f32_16x16x32_bf16 v[10:13], v[234:237], v[26:29], v[42:45]
	v_mfma_f32_16x16x32_bf16 v[50:53], v[238:241], v[50:53], v[10:13]
	v_mfma_f32_16x16x32_bf16 v[10:13], v[2:5], v[126:129], v[142:145]
	v_mfma_f32_16x16x32_bf16 v[42:45], v[212:215], v[150:153], v[10:13]
	v_mfma_f32_16x16x32_bf16 v[10:13], v[234:237], v[126:129], v[146:149]
	v_mfma_f32_16x16x32_bf16 v[34:37], v[238:241], v[150:153], v[10:13]
	v_mfma_f32_16x16x32_bf16 v[10:13], v[2:5], v[204:207], v[154:157]
	v_mfma_f32_16x16x32_bf16 v[26:29], v[212:215], v[208:211], v[10:13]
	v_mfma_f32_16x16x32_bf16 v[10:13], v[234:237], v[204:207], v[130:133]
	v_mfma_f32_16x16x32_bf16 v[2:5], v[2:5], v[216:219], v[178:181]
	v_mfma_f32_16x16x32_bf16 v[18:21], v[238:241], v[208:211], v[10:13]
	v_mfma_f32_16x16x32_bf16 v[10:13], v[212:215], v[222:225], v[2:5]
	v_mfma_f32_16x16x32_bf16 v[2:5], v[234:237], v[216:219], v[182:185]
	v_mfma_f32_16x16x32_bf16 v[2:5], v[238:241], v[222:225], v[2:5]
	s_setprio 0
	v_mov_b32_e32 v1, v189
	s_barrier
; __device__ __forceinline__ int opaque_tid() { int t = threadIdx.x; asm volatile("" : "+v"(t)); return t; }
;     __device__ __forceinline__ void operator()(const f32x4 (&acc)[2][2][4][2], const Unit& u, int wr, int wc, int fr, int fq) const {
;         { const int t_ = opaque_tid(); wr = t_ >> 8; wc = (t_ >> 6) & 3; fr = t_ & 15; fq = (t_ >> 4) & 3; }
;         const int row0 = u.pm * 256 + wr * 64 + fr - RL, col0 = u.pn * 256 + wc * 32 + 4 * fq;
; #pragma unroll
;         for (int ai = 0; ai < 2; ++ai)
; #pragma unroll
;             for (int m = 0; m < 4; ++m) {
;                 float* hp = PB + (size_t)(row0 + ai * 128 + m * 16) * 1024;
; #pragma unroll
;                 for (int bj = 0; bj < 2; ++bj)
; #pragma unroll
;                     for (int n = 0; n < 2; ++n) {
;                         const int c = col0 + bj * 128 + n * 16;
;                         const f32x4 g4 = *(const f32x4*)(gate + c);
	s_lshl_b32 s9, s9, 8
	v_lshrrev_b32_e32 v127, 1, v1
	v_lshrrev_b32_e32 v128, 2, v1
	v_and_b32_e32 v127, 0x60, v127
	v_and_b32_e32 v128, 12, v128
	v_or3_b32 v128, v127, s9, v128
	v_lshlrev_b32_e32 v128, 2, v128
	global_load_dwordx4 v[136:139], v128, s[4:5]
	global_load_dwordx4 v[140:143], v128, s[4:5] offset:64
	global_load_dwordx4 v[144:147], v128, s[4:5] offset:512
	global_load_dwordx4 v[148:151], v128, s[4:5] offset:576
	s_lshl_b32 s13, s13, 8
	v_ashrrev_i32_e32 v126, 2, v1
	s_addk_i32 s13, 0x8000
	v_and_b32_e32 v126, 0xffffffc0, v126
	v_and_or_b32 v1, v1, 15, s13
	v_add_u32_e32 v130, v1, v126
	v_ashrrev_i32_e32 v131, 31, v130
	v_lshlrev_b64 v[126:127], 12, v[130:131]
	s_mov_b32 s13, s12
	v_lshl_add_u64 v[126:127], s[2:3], 0, v[126:127]
	v_mov_b32_e32 v129, v0
	v_lshl_add_u64 v[126:127], v[126:127], 0, v[128:129]
	v_or_b32_e32 v1, 64, v128
	s_cmpk_gt_u32 s8, 0xff
	s_waitcnt vmcnt(0)
;     __device__ __forceinline__ void operator()(const f32x4 (&acc)[2][2][4][2], const Unit& u, int wr, int wc, int fr, int fq) const {
;     ...
;         for (int ai = 0; ai < 2; ++ai)
; #pragma unroll
;             for (int m = 0; m < 4; ++m) {
;                 float* hp = PB + (size_t)(row0 + ai * 128 + m * 16) * 1024;
; #pragma unroll
;                 for (int bj = 0; bj < 2; ++bj)
; #pragma unroll
;                     for (int n = 0; n < 2; ++n) {
;                         const int c = col0 + bj * 128 + n * 16;
;                         const f32x4 g4 = *(const f32x4*)(gate + c);
;                         *(f32x4*)(hp + c) = (g4 * coef) * acc[ai][bj][m][n];
;                     }
	v_pk_mul_f32 v[138:139], s[12:13], v[138:139]
	v_pk_mul_f32 v[136:137], s[14:15], v[136:137]
	v_pk_mul_f32 v[142:143], s[12:13], v[142:143]
	v_pk_mul_f32 v[140:141], s[14:15], v[140:141]
	v_pk_mul_f32 v[146:147], s[12:13], v[146:147]
	v_pk_mul_f32 v[144:145], s[14:15], v[144:145]
	v_pk_mul_f32 v[150:151], s[12:13], v[150:151]
	v_pk_mul_f32 v[148:149], s[14:15], v[148:149]
	v_pk_mul_f32 v[134:135], v[232:233], v[138:139]
	v_pk_mul_f32 v[132:133], v[230:231], v[136:137]
	global_store_dwordx4 v[126:127], v[132:135], off
	s_nop 1
	v_pk_mul_f32 v[124:125], v[124:125], v[142:143]
	v_pk_mul_f32 v[122:123], v[122:123], v[140:141]
	global_store_dwordx4 v[126:127], v[122:125], off offset:64
	s_nop 1
	v_or_b32_e32 v122, 0x200, v128
	v_pk_mul_f32 v[120:121], v[120:121], v[146:147]
	v_pk_mul_f32 v[118:119], v[118:119], v[144:145]
	global_store_dwordx4 v[126:127], v[118:121], off offset:512
	s_nop 1
	v_or_b32_e32 v118, 0x240, v128
	v_pk_mul_f32 v[116:117], v[116:117], v[150:151]
	v_pk_mul_f32 v[114:115], v[114:115], v[148:149]
	global_store_dwordx4 v[126:127], v[114:117], off offset:576
	s_nop 1
	v_or_b32_e32 v114, 16, v130
	v_ashrrev_i32_e32 v115, 31, v114
	v_lshlrev_b64 v[114:115], 12, v[114:115]
	v_lshl_add_u64 v[120:121], s[2:3], 0, v[114:115]
	v_pk_mul_f32 v[112:113], v[112:113], v[138:139]
	v_pk_mul_f32 v[110:111], v[110:111], v[136:137]
	v_lshl_add_u64 v[114:115], v[120:121], 0, v[128:129]
	global_store_dwordx4 v[114:115], v[110:113], off
	s_nop 1
	v_pk_mul_f32 v[100:101], v[100:101], v[142:143]
	v_pk_mul_f32 v[98:99], v[98:99], v[140:141]
	global_store_dwordx4 v[114:115], v[98:101], off offset:64
	s_nop 1
	v_pk_mul_f32 v[100:101], v[108:109], v[146:147]
	v_pk_mul_f32 v[98:99], v[106:107], v[144:145]
	global_store_dwordx4 v[114:115], v[98:101], off offset:512
	s_nop 1
	v_pk_mul_f32 v[100:101], v[104:105], v[150:151]
	v_pk_mul_f32 v[98:99], v[102:103], v[148:149]
	global_store_dwordx4 v[114:115], v[98:101], off offset:576
	s_nop 1
	v_or_b32_e32 v98, 32, v130
	v_ashrrev_i32_e32 v99, 31, v98
	v_lshlrev_b64 v[98:99], 12, v[98:99]
	v_lshl_add_u64 v[102:103], s[2:3], 0, v[98:99]
	v_pk_mul_f32 v[96:97], v[96:97], v[138:139]
	v_pk_mul_f32 v[94:95], v[94:95], v[136:137]
	v_lshl_add_u64 v[98:99], v[102:103], 0, v[128:129]
	global_store_dwordx4 v[98:99], v[94:97], off
	s_nop 1
	v_pk_mul_f32 v[84:85], v[84:85], v[142:143]
	v_pk_mul_f32 v[82:83], v[82:83], v[140:141]
	global_store_dwordx4 v[98:99], v[82:85], off offset:64
	s_nop 1
	v_pk_mul_f32 v[84:85], v[92:93], v[146:147]
	v_pk_mul_f32 v[82:83], v[90:91], v[144:145]
	global_store_dwordx4 v[98:99], v[82:85], off offset:512
	s_nop 1
	v_pk_mul_f32 v[84:85], v[88:89], v[150:151]
	v_pk_mul_f32 v[82:83], v[86:87], v[148:149]
	global_store_dwordx4 v[98:99], v[82:85], off offset:576
	s_nop 1
	v_or_b32_e32 v82, 48, v130
	v_ashrrev_i32_e32 v83, 31, v82
	v_lshlrev_b64 v[82:83], 12, v[82:83]
	v_lshl_add_u64 v[86:87], s[2:3], 0, v[82:83]
	s_mov_b64 s[2:3], 0x80000
	v_pk_mul_f32 v[80:81], v[80:81], v[138:139]
	v_pk_mul_f32 v[78:79], v[78:79], v[136:137]
	v_lshl_add_u64 v[82:83], v[86:87], 0, v[128:129]
	global_store_dwordx4 v[82:83], v[78:81], off
	s_nop 1
	v_pk_mul_f32 v[64:65], v[64:65], v[142:143]
	v_pk_mul_f32 v[62:63], v[62:63], v[140:141]
	global_store_dwordx4 v[82:83], v[62:65], off offset:64
	s_nop 1
	v_pk_mul_f32 v[64:65], v[76:77], v[146:147]
	v_pk_mul_f32 v[62:63], v[74:75], v[144:145]
	global_store_dwordx4 v[82:83], v[62:65], off offset:512
	s_nop 1
	v_pk_mul_f32 v[64:65], v[68:69], v[150:151]
	v_pk_mul_f32 v[62:63], v[66:67], v[148:149]
	global_store_dwordx4 v[82:83], v[62:65], off offset:576
	s_nop 1
	v_lshl_add_u64 v[66:67], v[126:127], 0, s[2:3]
	s_mov_b32 s2, 0x80000
	v_add_co_u32_e32 v68, vcc, s2, v126
	s_mov_b64 s[2:3], 0x90000
	s_nop 0
	v_addc_co_u32_e32 v69, vcc, 0, v127, vcc
	v_pk_mul_f32 v[64:65], v[72:73], v[138:139]
	v_pk_mul_f32 v[62:63], v[70:71], v[136:137]
	global_store_dwordx4 v[68:69], v[62:65], off
	s_nop 1
	v_pk_mul_f32 v[56:57], v[56:57], v[142:143]
	v_pk_mul_f32 v[54:55], v[54:55], v[140:141]
	global_store_dwordx4 v[66:67], v[54:57], off offset:64
	s_nop 1
	v_pk_mul_f32 v[56:57], v[60:61], v[146:147]
	v_pk_mul_f32 v[54:55], v[58:59], v[144:145]
	global_store_dwordx4 v[66:67], v[54:57], off offset:512
	s_nop 1
	v_pk_mul_f32 v[52:53], v[52:53], v[150:151]
	v_pk_mul_f32 v[50:51], v[50:51], v[148:149]
	global_store_dwordx4 v[66:67], v[50:53], off offset:576
	s_nop 1
	v_pk_mul_f32 v[46:47], v[46:47], v[136:137]
	v_lshl_add_u64 v[50:51], v[126:127], 0, s[2:3]
	s_mov_b32 s2, 0x90000
	v_pk_mul_f32 v[48:49], v[48:49], v[138:139]
	v_add_co_u32_e32 v52, vcc, s2, v126
	s_mov_b64 s[2:3], 0xa0000
	s_nop 0
	v_addc_co_u32_e32 v53, vcc, 0, v127, vcc
	global_store_dwordx4 v[52:53], v[46:49], off
	s_nop 1
	v_pk_mul_f32 v[40:41], v[40:41], v[142:143]
	v_pk_mul_f32 v[38:39], v[38:39], v[140:141]
	global_store_dwordx4 v[50:51], v[38:41], off offset:64
	s_nop 1
	v_pk_mul_f32 v[40:41], v[44:45], v[146:147]
	v_pk_mul_f32 v[38:39], v[42:43], v[144:145]
	global_store_dwordx4 v[50:51], v[38:41], off offset:512
	s_nop 1
	v_pk_mul_f32 v[36:37], v[36:37], v[150:151]
	v_pk_mul_f32 v[34:35], v[34:35], v[148:149]
	global_store_dwordx4 v[50:51], v[34:37], off offset:576
	s_nop 1
	v_pk_mul_f32 v[30:31], v[30:31], v[136:137]
	v_lshl_add_u64 v[34:35], v[126:127], 0, s[2:3]
	s_mov_b32 s2, 0xa0000
	v_pk_mul_f32 v[32:33], v[32:33], v[138:139]
	v_add_co_u32_e32 v36, vcc, s2, v126
	s_mov_b64 s[2:3], 0xb0000
	s_nop 0
	v_addc_co_u32_e32 v37, vcc, 0, v127, vcc
	global_store_dwordx4 v[36:37], v[30:33], off
	s_nop 1
	v_pk_mul_f32 v[24:25], v[24:25], v[142:143]
	v_pk_mul_f32 v[22:23], v[22:23], v[140:141]
	global_store_dwordx4 v[34:35], v[22:25], off offset:64
	s_nop 1
	v_pk_mul_f32 v[24:25], v[28:29], v[146:147]
	v_pk_mul_f32 v[22:23], v[26:27], v[144:145]
	global_store_dwordx4 v[34:35], v[22:25], off offset:512
	s_nop 1
	v_pk_mul_f32 v[20:21], v[20:21], v[150:151]
	v_pk_mul_f32 v[18:19], v[18:19], v[148:149]
	global_store_dwordx4 v[34:35], v[18:21], off offset:576
	s_nop 1
	v_pk_mul_f32 v[14:15], v[14:15], v[136:137]
	v_lshl_add_u64 v[18:19], v[126:127], 0, s[2:3]
	s_mov_b32 s2, 0xb0000
	v_pk_mul_f32 v[16:17], v[16:17], v[138:139]
	v_add_co_u32_e32 v20, vcc, s2, v126
	s_nop 1
	v_addc_co_u32_e32 v21, vcc, 0, v127, vcc
	global_store_dwordx4 v[20:21], v[14:17], off
	s_nop 1
	v_pk_mul_f32 v[8:9], v[8:9], v[142:143]
	v_pk_mul_f32 v[6:7], v[6:7], v[140:141]
	global_store_dwordx4 v[18:19], v[6:9], off offset:64
	s_nop 1
	v_pk_mul_f32 v[8:9], v[12:13], v[146:147]
	v_pk_mul_f32 v[6:7], v[10:11], v[144:145]
	global_store_dwordx4 v[18:19], v[6:9], off offset:512
	s_nop 1
	v_pk_mul_f32 v[4:5], v[4:5], v[150:151]
	v_pk_mul_f32 v[2:3], v[2:3], v[148:149]
	global_store_dwordx4 v[18:19], v[2:5], off offset:576
	s_nop 1
	s_waitcnt vmcnt(0)
	s_cbranch_scc1 .LBB0_606
	s_barrier
	s_branch .LBB0_606
